# u-pass with two groups of gathers in flight per wave (second ring in the former x-fragment registers, x fragments read from the LDS image for all k-steps, staging and re-request interleaved per slot,
# speedup vs baseline: 1.0094x; 1.0078x over previous
; #define LAS __attribute__((address_space(3)))
; #define ULOADA(slot, ereg, lb, j_) { const int ea_ = __builtin_amdgcn_readlane((ereg), (lb) + 2 * (j_)), eb_ = __builtin_amdgcn_readlane((ereg), (lb) + 2 * (j_) + 1); const int el_ = hh ? eb_ : ea_; \
;         ring[slot] = *(const GAS v4u*)(U4 + (((unsigned)el_ << 9) + laneoff)); }
; __device__ __forceinline__ void phase_gather_u_mfma(LAS unsigned char* lds, const bf16* X, const int* EID, float* GATE, const unsigned char* U4, const float* DQU, const float* DQV) {
;     const int tid = threadIdx.x, lane = tid & 63, wave = __builtin_amdgcn_readfirstlane(tid >> 6);
;     const int gw = blockIdx.x * NWAVES + wave, NGW = gridDim.x * NWAVES;
;     const int n = lane & 31, hh = lane >> 5;
;     LAS unsigned char* rows = lds + wave * 18048;
;     LAS unsigned char* x8 = rows + 16896;
;     const unsigned laneoff = 16u * (unsigned)n;
;     int t = gw;
;     if (t < T) {
;     int e0 = EID[(size_t)t * 128 + lane], e1 = EID[(size_t)t * 128 + 64 + lane];
;     v4u ring[16];
;     ...
; #pragma unroll
;     for (int j = 0; j < 16; ++j) ULOADA(j, e0, 0, j)
.LBB0_927:
	s_cmp_lt_i32 s68, 9
	s_cselect_b64 s[8:9], -1, 0
	s_and_b64 s[0:1], s[8:9], s[6:7]
	s_andn2_b64 vcc, exec, s[0:1]
	s_cbranch_vccnz .LBB0_957
	v_readfirstlane_b32 s1, v0
	s_lshl_b32 s0, s88, 3
	s_lshr_b32 s2, s1, 6
	s_add_i32 s18, s2, s0
	s_cmpk_gt_i32 s18, 0x7fff
	s_cbranch_scc1 .LBB0_957
	s_add_u32 s0, s82, 0x2000000
	s_addc_u32 s1, s83, 0
	s_add_u32 s10, s82, 0x1d00000
	s_addc_u32 s11, s83, 0
	s_add_u32 s12, s82, 0x1d20000
	s_waitcnt vmcnt(0)
	v_and_b32_e32 v3, 63, v0
	s_addc_u32 s13, s83, 0
	v_lshlrev_b32_e32 v4, 2, v3
	v_mov_b32_e32 v5, 0
	s_ashr_i32 s19, s18, 31
	v_lshl_add_u64 v[146:147], s[60:61], 0, v[4:5]
	s_lshl_b64 s[4:5], s[18:19], 9
	v_lshl_add_u64 v[6:7], v[146:147], 0, s[4:5]
	global_load_dword v2, v[6:7], off nt
	global_load_dword v154, v[6:7], off offset:256 nt
	v_and_b32_e32 v8, 31, v0
	v_lshlrev_b32_e32 v1, 4, v8
	s_mulk_i32 s2, 0x4680
	v_lshl_add_u64 v[148:149], s[70:71], 0, v[4:5]
	v_lshlrev_b32_e32 v156, 4, v186
	v_mov_b32_e32 v159, 0x7f7f7f7f
	v_mov_b32_e32 v160, 0x3ba10414
	s_brev_b32 s33, -2
	v_mov_b32_e32 v164, 0xb9c68948
	v_mov_b32_e32 v165, 0x7f800000
	s_waitcnt vmcnt(0)
	v_cmp_gt_u32_e64 s[4:5], 32, v3
	s_add_i32 s21, s2, 0
	s_movk_i32 s3, 0x210
	v_mov_b32_e32 v4, s21
	v_lshlrev_b32_e32 v7, 4, v3
	v_mad_u32_u24 v9, v186, s3, v4
	v_mad_u32_u24 v10, v8, s3, v4
	v_lshlrev_b32_e32 v4, 5, v3
	v_mov_b32_e32 v3, s2
	v_readlane_b32 s6, v255, 9
	v_mad_u32_u24 v3, v8, s3, v3
	v_readlane_b32 s7, v255, 10
	v_lshlrev_b32_e32 v6, 2, v8
	v_add3_u32 v3, v3, v156, 0
	s_lshl_b32 s20, s6, 3
	v_cmp_eq_u32_e64 s[6:7], 0, v8
	v_lshl_add_u64 v[150:151], s[62:63], 0, v[4:5]
	v_add_u32_e32 v157, 0x100, v3
	s_add_i32 s22, s21, 0x4400
	v_add_u32_e32 v158, s21, v7
	s_mov_b32 s23, 0x378e98ab
	s_mov_b32 s24, 0x3b7cd369
	s_mov_b32 s25, 0xbcc618b2
	s_mov_b32 s26, 0x3dda74e4
	s_mov_b32 s27, 0x3f228afd
	s_mov_b32 s28, 0x3e03c728
	s_mov_b32 s29, 0xbfb8aa3b
	s_mov_b32 s30, 0x42ce8ed0
	s_mov_b32 s31, 0xc2b17218
	v_add_u32_e32 v161, v9, v1
	v_add_u32_e32 v162, v10, v156
	v_add_u32_e32 v163, s21, v6
	v_lshlrev_b32_e32 v226, 2, v186
	v_add_u32_e32 v227, 0x80, v226
	s_ashr_i32 s3, s18, 31
	s_mov_b32 s2, s18
	s_lshl_b64 s[2:3], s[2:3], 11
	v_lshl_add_u64 v[228:229], v[150:151], 0, s[2:3]
	global_load_dwordx4 v[212:215], v[228:229], off nt
	global_load_dwordx4 v[216:219], v[228:229], off offset:16 nt
	s_ashr_i32 s3, s18, 31
	s_mov_b32 s2, s18
	s_lshl_b64 s[2:3], s[2:3], 9
	v_lshl_add_u64 v[228:229], v[148:149], 0, s[2:3]
	global_load_dword v220, v[228:229], off nt
	global_load_dword v221, v[228:229], off offset:256 nt
	v_mov_b32_e32 v228, v2
	v_ashrrev_i32_e32 v229, 31, v2
	v_lshlrev_b64 v[228:229], 3, v[228:229]
	v_lshl_add_u64 v[228:229], s[10:11], 0, v[228:229]
	global_load_dwordx2 v[222:223], v[228:229], off
	v_mov_b32_e32 v228, v154
	v_ashrrev_i32_e32 v229, 31, v154
	v_lshlrev_b64 v[228:229], 3, v[228:229]
	v_lshl_add_u64 v[228:229], s[10:11], 0, v[228:229]
	global_load_dwordx2 v[224:225], v[228:229], off
	ds_bpermute_b32 v82, v226, v2
	ds_bpermute_b32 v86, v226, v2 offset:8
	ds_bpermute_b32 v90, v226, v2 offset:16
	ds_bpermute_b32 v94, v226, v2 offset:24
	ds_bpermute_b32 v98, v226, v2 offset:32
	ds_bpermute_b32 v102, v226, v2 offset:40
	ds_bpermute_b32 v106, v226, v2 offset:48
	ds_bpermute_b32 v110, v226, v2 offset:56
	ds_bpermute_b32 v114, v226, v2 offset:64
	ds_bpermute_b32 v118, v226, v2 offset:72
	ds_bpermute_b32 v122, v226, v2 offset:80
	ds_bpermute_b32 v126, v226, v2 offset:88
	ds_bpermute_b32 v130, v226, v2 offset:96
	ds_bpermute_b32 v134, v226, v2 offset:104
	ds_bpermute_b32 v138, v226, v2 offset:112
	ds_bpermute_b32 v142, v226, v2 offset:120
	s_waitcnt lgkmcnt(15)
	v_lshl_or_b32 v82, v82, 9, v1
	global_load_dwordx4 v[82:85], v82, s[0:1]
	s_waitcnt lgkmcnt(14)
; #define ULOADA(slot, ereg, lb, j_) { const int ea_ = __builtin_amdgcn_readlane((ereg), (lb) + 2 * (j_)), eb_ = __builtin_amdgcn_readlane((ereg), (lb) + 2 * (j_) + 1); const int el_ = hh ? eb_ : ea_; \
;         ring[slot] = *(const GAS v4u*)(U4 + (((unsigned)el_ << 9) + laneoff)); }
; __device__ __forceinline__ void phase_gather_u_mfma(LAS unsigned char* lds, const bf16* X, const int* EID, float* GATE, const unsigned char* U4, const float* DQU, const float* DQV) {
;     ...
; #pragma unroll
;     for (int j = 0; j < 16; ++j) ULOADA(j, e0, 0, j)
;     ...
;             { const int qn = q + 1;
;               const int er = (qn >= 4) ? ne0 : ((qn >> 1) ? e1 : e0); const int lb = (qn >= 4) ? 0 : 32 * (qn & 1);
; #pragma unroll
;               for (int j = 0; j < 16; ++j) ULOADA(j, er, lb, j) }
	v_lshl_or_b32 v86, v86, 9, v1
	global_load_dwordx4 v[86:89], v86, s[0:1]
	s_waitcnt lgkmcnt(13)
	v_lshl_or_b32 v90, v90, 9, v1
	global_load_dwordx4 v[90:93], v90, s[0:1]
	s_waitcnt lgkmcnt(12)
	v_lshl_or_b32 v94, v94, 9, v1
	global_load_dwordx4 v[94:97], v94, s[0:1]
	s_waitcnt lgkmcnt(11)
	v_lshl_or_b32 v98, v98, 9, v1
	global_load_dwordx4 v[98:101], v98, s[0:1]
	s_waitcnt lgkmcnt(10)
	v_lshl_or_b32 v102, v102, 9, v1
	global_load_dwordx4 v[102:105], v102, s[0:1]
	s_waitcnt lgkmcnt(9)
	v_lshl_or_b32 v106, v106, 9, v1
	global_load_dwordx4 v[106:109], v106, s[0:1]
	s_waitcnt lgkmcnt(8)
	v_lshl_or_b32 v110, v110, 9, v1
	global_load_dwordx4 v[110:113], v110, s[0:1]
	s_waitcnt lgkmcnt(7)
	v_lshl_or_b32 v114, v114, 9, v1
	global_load_dwordx4 v[114:117], v114, s[0:1]
	s_waitcnt lgkmcnt(6)
	v_lshl_or_b32 v118, v118, 9, v1
	global_load_dwordx4 v[118:121], v118, s[0:1]
	s_waitcnt lgkmcnt(5)
	v_lshl_or_b32 v122, v122, 9, v1
	global_load_dwordx4 v[122:125], v122, s[0:1]
	s_waitcnt lgkmcnt(4)
	v_lshl_or_b32 v126, v126, 9, v1
	global_load_dwordx4 v[126:129], v126, s[0:1]
	s_waitcnt lgkmcnt(3)
	v_lshl_or_b32 v130, v130, 9, v1
	global_load_dwordx4 v[130:133], v130, s[0:1]
	s_waitcnt lgkmcnt(2)
	v_lshl_or_b32 v134, v134, 9, v1
	global_load_dwordx4 v[134:137], v134, s[0:1]
	s_waitcnt lgkmcnt(1)
	v_lshl_or_b32 v138, v138, 9, v1
	global_load_dwordx4 v[138:141], v138, s[0:1]
	s_waitcnt lgkmcnt(0)
	v_lshl_or_b32 v142, v142, 9, v1
	global_load_dwordx4 v[142:145], v142, s[0:1]
	ds_bpermute_b32 v18, v227, v2
	ds_bpermute_b32 v22, v227, v2 offset:8
	ds_bpermute_b32 v26, v227, v2 offset:16
	ds_bpermute_b32 v30, v227, v2 offset:24
	ds_bpermute_b32 v34, v227, v2 offset:32
	ds_bpermute_b32 v38, v227, v2 offset:40
	ds_bpermute_b32 v42, v227, v2 offset:48
	ds_bpermute_b32 v46, v227, v2 offset:56
	ds_bpermute_b32 v50, v227, v2 offset:64
	ds_bpermute_b32 v54, v227, v2 offset:72
	ds_bpermute_b32 v58, v227, v2 offset:80
	ds_bpermute_b32 v62, v227, v2 offset:88
	ds_bpermute_b32 v66, v227, v2 offset:96
	ds_bpermute_b32 v70, v227, v2 offset:104
	ds_bpermute_b32 v74, v227, v2 offset:112
	ds_bpermute_b32 v78, v227, v2 offset:120
	s_waitcnt lgkmcnt(15)
	v_lshl_or_b32 v18, v18, 9, v1
	global_load_dwordx4 v[18:21], v18, s[0:1]
	s_waitcnt lgkmcnt(14)
	v_lshl_or_b32 v22, v22, 9, v1
	global_load_dwordx4 v[22:25], v22, s[0:1]
	s_waitcnt lgkmcnt(13)
	v_lshl_or_b32 v26, v26, 9, v1
	global_load_dwordx4 v[26:29], v26, s[0:1]
	s_waitcnt lgkmcnt(12)
	v_lshl_or_b32 v30, v30, 9, v1
	global_load_dwordx4 v[30:33], v30, s[0:1]
	s_waitcnt lgkmcnt(11)
	v_lshl_or_b32 v34, v34, 9, v1
	global_load_dwordx4 v[34:37], v34, s[0:1]
	s_waitcnt lgkmcnt(10)
	v_lshl_or_b32 v38, v38, 9, v1
	global_load_dwordx4 v[38:41], v38, s[0:1]
	s_waitcnt lgkmcnt(9)
	v_lshl_or_b32 v42, v42, 9, v1
	global_load_dwordx4 v[42:45], v42, s[0:1]
	s_waitcnt lgkmcnt(8)
	v_lshl_or_b32 v46, v46, 9, v1
	global_load_dwordx4 v[46:49], v46, s[0:1]
	s_waitcnt lgkmcnt(7)
	v_lshl_or_b32 v50, v50, 9, v1
	global_load_dwordx4 v[50:53], v50, s[0:1]
	s_waitcnt lgkmcnt(6)
	v_lshl_or_b32 v54, v54, 9, v1
	global_load_dwordx4 v[54:57], v54, s[0:1]
	s_waitcnt lgkmcnt(5)
	v_lshl_or_b32 v58, v58, 9, v1
	global_load_dwordx4 v[58:61], v58, s[0:1]
	s_waitcnt lgkmcnt(4)
	v_lshl_or_b32 v62, v62, 9, v1
	global_load_dwordx4 v[62:65], v62, s[0:1]
	s_waitcnt lgkmcnt(3)
	v_lshl_or_b32 v66, v66, 9, v1
	global_load_dwordx4 v[66:69], v66, s[0:1]
	s_waitcnt lgkmcnt(2)
	v_lshl_or_b32 v70, v70, 9, v1
	global_load_dwordx4 v[70:73], v70, s[0:1]
	s_waitcnt lgkmcnt(1)
	v_lshl_or_b32 v74, v74, 9, v1
	global_load_dwordx4 v[74:77], v74, s[0:1]
	s_waitcnt lgkmcnt(0)
	v_lshl_or_b32 v78, v78, 9, v1
	global_load_dwordx4 v[78:81], v78, s[0:1]
	s_branch .LBB0_931

; #define GAS __attribute__((address_space(1)))
; #define LAS __attribute__((address_space(3)))
; __device__ __forceinline__ void phase_gather_u_mfma(LAS unsigned char* lds, const bf16* X, const int* EID, float* GATE, const unsigned char* U4, const float* DQU, const float* DQV) {
;     ...
;     for (;;) {
;         const int tn = t + NGW; const bool has_next = tn < T;
;         int ne0 = e0, ne1 = e1;
;         if (has_next) { ne0 = EID[(size_t)tn * 128 + lane]; ne1 = EID[(size_t)tn * 128 + 64 + lane]; }
;         const float gt0 = GATE[(size_t)t * 128 + lane], gt1 = GATE[(size_t)t * 128 + 64 + lane];
;         const float dqu0 = DQU[e0], dqu1 = DQU[e1], dqv0 = DQV[e0], dqv1 = DQV[e1];
;         { const v4u xa = *((const GAS v4u*)(X + (size_t)t * D) + 2 * lane), xb = *((const GAS v4u*)(X + (size_t)t * D) + 2 * lane + 1);
;           int w0 = 0, w1 = 0, w2 = 0, w3 = 0;
;           w0 = __builtin_amdgcn_cvt_pk_fp8_f32(bflo(xa.x), bfhi(xa.x), w0, false); w0 = __builtin_amdgcn_cvt_pk_fp8_f32(bflo(xa.y), bfhi(xa.y), w0, true);
;           w1 = __builtin_amdgcn_cvt_pk_fp8_f32(bflo(xa.z), bfhi(xa.z), w1, false); w1 = __builtin_amdgcn_cvt_pk_fp8_f32(bflo(xa.w), bfhi(xa.w), w1, true);
;           w2 = __builtin_amdgcn_cvt_pk_fp8_f32(bflo(xb.x), bfhi(xb.x), w2, false); w2 = __builtin_amdgcn_cvt_pk_fp8_f32(bflo(xb.y), bfhi(xb.y), w2, true);
;           w3 = __builtin_amdgcn_cvt_pk_fp8_f32(bflo(xb.z), bfhi(xb.z), w3, false); w3 = __builtin_amdgcn_cvt_pk_fp8_f32(bflo(xb.w), bfhi(xb.w), w3, true);
;           *(LAS v4u*)(x8 + 16 * lane) = (v4u){(unsigned)w0, (unsigned)w1, (unsigned)w2, (unsigned)w3}; }
;         float act0 = 0.f, act1 = 0.f;
;         v4u xf0[8], xf1[8];
; #pragma unroll
;         for (int ks = 0; ks < 8; ++ks) { xf0[ks] = *(const LAS v4u*)(x8 + 16 * hh + 64 * ks); xf1[ks] = *(const LAS v4u*)(x8 + 16 * hh + 64 * ks + 32); }
;         for (int q = 0; q < 4; ++q) {
; #pragma unroll
;             for (int j = 0; j < 16; ++j) *(LAS v4u*)(rows + hh * 528 + 16 * n + j * 1056) = ring[j];
;             __builtin_amdgcn_sched_barrier(0);
;             { const int qn = q + 1;
;               const int er = (qn >= 4) ? ne0 : ((qn >> 1) ? e1 : e0); const int lb = (qn >= 4) ? 0 : 32 * (qn & 1);
; #pragma unroll
;               for (int j = 0; j < 16; ++j) ULOADA(j, er, lb, j) }
.LBB0_931:
	s_add_i32 s14, s18, s20
	s_cmpk_gt_i32 s14, 0x7fff
	s_cselect_b64 s[16:17], -1, 0
	s_cselect_b32 s15, s18, s14
	s_ashr_i32 s3, s15, 31
	s_mov_b32 s2, s15
	s_lshl_b64 s[2:3], s[2:3], 9
	v_lshl_add_u64 v[4:5], v[146:147], 0, s[2:3]
	global_load_dword v166, v[4:5], off nt
	global_load_dword v167, v[4:5], off offset:256 nt
	s_waitcnt vmcnt(34)
	v_mov_b32_e32 v4, v212
	v_mov_b32_e32 v5, v213
	v_mov_b32_e32 v6, v214
	v_mov_b32_e32 v7, v215
	v_mov_b32_e32 v8, v216
	v_mov_b32_e32 v9, v217
	v_mov_b32_e32 v10, v218
	v_mov_b32_e32 v11, v219
	v_mov_b32_e32 v169, v220
	v_mov_b32_e32 v155, v221
	v_mov_b32_e32 v208, v222
	v_mov_b32_e32 v209, v223
	v_mov_b32_e32 v210, v224
	v_mov_b32_e32 v211, v225
	s_ashr_i32 s19, s18, 31
	s_lshl_b64 s[2:3], s[18:19], 9
	v_lshl_add_u64 v[152:153], v[148:149], 0, s[2:3]
	v_add_u32_e32 v173, s21, v156
	v_mov_b32_e32 v12, 0
	v_mov_b32_e32 v13, 0
	v_mov_b32_e32 v14, 0
	v_mov_b32_e32 v15, 0
	v_lshlrev_b32_e32 v3, 16, v4
	v_and_b32_e32 v4, 0xffff0000, v4
	v_lshlrev_b32_e32 v17, 16, v6
	v_and_b32_e32 v6, 0xffff0000, v6
	v_lshlrev_b32_e32 v170, 16, v8
	v_and_b32_e32 v8, 0xffff0000, v8
	v_lshlrev_b32_e32 v172, 16, v10
	v_and_b32_e32 v10, 0xffff0000, v10
	v_cvt_pk_fp8_f32 v12, v3, v4
	v_cvt_pk_fp8_f32 v13, v17, v6
	v_cvt_pk_fp8_f32 v14, v170, v8
	v_cvt_pk_fp8_f32 v15, v172, v10
	v_lshlrev_b32_e32 v16, 16, v5
	v_and_b32_e32 v5, 0xffff0000, v5
	v_lshlrev_b32_e32 v168, 16, v7
	v_and_b32_e32 v7, 0xffff0000, v7
	v_lshlrev_b32_e32 v171, 16, v9
	v_and_b32_e32 v9, 0xffff0000, v9
	v_lshlrev_b32_e32 v185, 16, v11
	v_and_b32_e32 v11, 0xffff0000, v11
	v_cvt_pk_fp8_f32 v12, v16, v5 op_sel:[0,0,1]
	v_cvt_pk_fp8_f32 v13, v168, v7 op_sel:[0,0,1]
	v_cvt_pk_fp8_f32 v14, v171, v9 op_sel:[0,0,1]
	v_cvt_pk_fp8_f32 v15, v185, v11 op_sel:[0,0,1]
	ds_write_b128 v158, v[12:15] offset:16896
	v_readlane_b32 s2, v154, 0
	v_readlane_b32 s3, v154, 1
	s_waitcnt vmcnt(33)
	ds_write_b128 v161, v[82:85]
	v_mov_b32_e32 v248, s3
	v_mov_b32_e32 v235, s2
	v_cndmask_b32_e64 v248, v248, v235, s[4:5]
	v_lshl_or_b32 v248, v248, 9, v1
	global_load_dwordx4 v[82:85], v248, s[0:1]
	v_readlane_b32 s2, v154, 2
	v_readlane_b32 s3, v154, 3
	s_waitcnt vmcnt(33)
	ds_write_b128 v161, v[86:89] offset:1056
	v_mov_b32_e32 v249, s3
	v_mov_b32_e32 v235, s2
	v_cndmask_b32_e64 v249, v249, v235, s[4:5]
	v_lshl_or_b32 v249, v249, 9, v1
	global_load_dwordx4 v[86:89], v249, s[0:1]
	v_readlane_b32 s2, v154, 4
	v_readlane_b32 s3, v154, 5
	s_waitcnt vmcnt(33)
	ds_write_b128 v161, v[90:93] offset:2112
	v_mov_b32_e32 v250, s3
	v_mov_b32_e32 v235, s2
	v_cndmask_b32_e64 v250, v250, v235, s[4:5]
	v_lshl_or_b32 v250, v250, 9, v1
	global_load_dwordx4 v[90:93], v250, s[0:1]
	v_readlane_b32 s2, v154, 6
	v_readlane_b32 s3, v154, 7
	s_waitcnt vmcnt(33)
	ds_write_b128 v161, v[94:97] offset:3168
	v_mov_b32_e32 v251, s3
	v_mov_b32_e32 v235, s2
	v_cndmask_b32_e64 v251, v251, v235, s[4:5]
	v_lshl_or_b32 v251, v251, 9, v1
	global_load_dwordx4 v[94:97], v251, s[0:1]
	v_readlane_b32 s2, v154, 8
	v_readlane_b32 s3, v154, 9
	s_waitcnt vmcnt(33)
	ds_write_b128 v161, v[98:101] offset:4224
	v_mov_b32_e32 v252, s3
	v_mov_b32_e32 v235, s2
	v_cndmask_b32_e64 v252, v252, v235, s[4:5]
	v_lshl_or_b32 v252, v252, 9, v1
	global_load_dwordx4 v[98:101], v252, s[0:1]
	v_readlane_b32 s2, v154, 10
	v_readlane_b32 s3, v154, 11
	s_waitcnt vmcnt(33)
	ds_write_b128 v161, v[102:105] offset:5280
	v_mov_b32_e32 v253, s3
	v_mov_b32_e32 v235, s2
	v_cndmask_b32_e64 v253, v253, v235, s[4:5]
	v_lshl_or_b32 v253, v253, 9, v1
	global_load_dwordx4 v[102:105], v253, s[0:1]
	v_readlane_b32 s2, v154, 12
	v_readlane_b32 s3, v154, 13
	s_waitcnt vmcnt(33)
	ds_write_b128 v161, v[106:109] offset:6336
	v_mov_b32_e32 v254, s3
	v_mov_b32_e32 v235, s2
	v_cndmask_b32_e64 v254, v254, v235, s[4:5]
	v_lshl_or_b32 v254, v254, 9, v1
	global_load_dwordx4 v[106:109], v254, s[0:1]
	v_readlane_b32 s2, v154, 14
	v_readlane_b32 s3, v154, 15
	s_waitcnt vmcnt(33)
	ds_write_b128 v161, v[110:113] offset:7392
	v_mov_b32_e32 v204, s3
	v_mov_b32_e32 v235, s2
	v_cndmask_b32_e64 v204, v204, v235, s[4:5]
	v_lshl_or_b32 v204, v204, 9, v1
	global_load_dwordx4 v[110:113], v204, s[0:1]
	v_readlane_b32 s2, v154, 16
	v_readlane_b32 s3, v154, 17
	s_waitcnt vmcnt(33)
	ds_write_b128 v161, v[114:117] offset:8448
	v_mov_b32_e32 v205, s3
	v_mov_b32_e32 v235, s2
	v_cndmask_b32_e64 v205, v205, v235, s[4:5]
	v_lshl_or_b32 v205, v205, 9, v1
	global_load_dwordx4 v[114:117], v205, s[0:1]
	v_readlane_b32 s2, v154, 18
	v_readlane_b32 s3, v154, 19
	s_waitcnt vmcnt(33)
	ds_write_b128 v161, v[118:121] offset:9504
	v_mov_b32_e32 v206, s3
	v_mov_b32_e32 v235, s2
	v_cndmask_b32_e64 v206, v206, v235, s[4:5]
	v_lshl_or_b32 v206, v206, 9, v1
	global_load_dwordx4 v[118:121], v206, s[0:1]
	v_readlane_b32 s2, v154, 20
	v_readlane_b32 s3, v154, 21
	s_waitcnt vmcnt(33)
	ds_write_b128 v161, v[122:125] offset:10560
	v_mov_b32_e32 v207, s3
	v_mov_b32_e32 v235, s2
	v_cndmask_b32_e64 v207, v207, v235, s[4:5]
	v_lshl_or_b32 v207, v207, 9, v1
	global_load_dwordx4 v[122:125], v207, s[0:1]
	v_readlane_b32 s2, v154, 22
	v_readlane_b32 s3, v154, 23
	s_waitcnt vmcnt(33)
	ds_write_b128 v161, v[126:129] offset:11616
	v_mov_b32_e32 v230, s3
	v_mov_b32_e32 v235, s2
	v_cndmask_b32_e64 v230, v230, v235, s[4:5]
	v_lshl_or_b32 v230, v230, 9, v1
	global_load_dwordx4 v[126:129], v230, s[0:1]
	v_readlane_b32 s2, v154, 24
	v_readlane_b32 s3, v154, 25
	s_waitcnt vmcnt(33)
	ds_write_b128 v161, v[130:133] offset:12672
	v_mov_b32_e32 v231, s3
	v_mov_b32_e32 v235, s2
	v_cndmask_b32_e64 v231, v231, v235, s[4:5]
	v_lshl_or_b32 v231, v231, 9, v1
	global_load_dwordx4 v[130:133], v231, s[0:1]
	v_readlane_b32 s2, v154, 26
	v_readlane_b32 s3, v154, 27
	s_waitcnt vmcnt(33)
; __device__ __forceinline__ void phase_gather_u_mfma(LAS unsigned char* lds, const bf16* X, const int* EID, float* GATE, const unsigned char* U4, const float* DQU, const float* DQV) {
;     ...
;         for (int q = 0; q < 4; ++q) {
; #pragma unroll
;             for (int j = 0; j < 16; ++j) *(LAS v4u*)(rows + hh * 528 + 16 * n + j * 1056) = ring[j];
;             __builtin_amdgcn_sched_barrier(0);
;             { const int qn = q + 1;
;               const int er = (qn >= 4) ? ne0 : ((qn >> 1) ? e1 : e0); const int lb = (qn >= 4) ? 0 : 32 * (qn & 1);
; #pragma unroll
;               for (int j = 0; j < 16; ++j) ULOADA(j, er, lb, j) }
;             __builtin_amdgcn_sched_barrier(0);
;             f32x16 acc;
; #pragma unroll
;             for (int r = 0; r < 16; ++r) acc[r] = 0.f;
; #pragma unroll
;             for (int ks = 0; ks < 8; ++ks) {
;                 const v4u a4 = *(const LAS v4u*)(rows + n * 528 + 16 * hh + 32 * ks);
;                 v8i A, B;
;                 A[0] = (int)a4.x; A[1] = (int)a4.y; A[2] = (int)a4.z; A[3] = (int)a4.w; A[4] = 0; A[5] = 0; A[6] = 0; A[7] = 0;
;                 B[0] = (int)xf0[ks].x; B[1] = (int)xf0[ks].y; B[2] = (int)xf0[ks].z; B[3] = (int)xf0[ks].w; B[4] = (int)xf1[ks].x; B[5] = (int)xf1[ks].y; B[6] = (int)xf1[ks].z; B[7] = (int)xf1[ks].w;
;                 acc = __builtin_amdgcn_mfma_scale_f32_32x32x64_f8f6f4(A, B, acc, 4, 0, 0, 0x7f7f7f7f, 0, 0x7f7f7f7f);
;                 if ((ks & 1) == 1) __builtin_amdgcn_sched_barrier(0);
;             }
;             unsigned xo = 16u * (unsigned)hh; asm volatile("" : "+v"(xo));
; #pragma unroll 2
;             for (int ks = 8; ks < 16; ++ks) {
;                 const v4u a4 = *(const LAS v4u*)(rows + n * 528 + 16 * hh + 32 * ks);
;                 const v4u b0 = *(const LAS v4u*)(x8 + xo + 64 * ks), b1 = *(const LAS v4u*)(x8 + xo + 64 * ks + 32);
;                 v8i A, B;
;                 A[0] = (int)a4.x; A[1] = (int)a4.y; A[2] = (int)a4.z; A[3] = (int)a4.w; A[4] = 0; A[5] = 0; A[6] = 0; A[7] = 0;
;                 B[0] = (int)b0.x; B[1] = (int)b0.y; B[2] = (int)b0.z; B[3] = (int)b0.w; B[4] = (int)b1.x; B[5] = (int)b1.y; B[6] = (int)b1.z; B[7] = (int)b1.w;
;                 acc = __builtin_amdgcn_mfma_scale_f32_32x32x64_f8f6f4(A, B, acc, 4, 0, 0, 0x7f7f7f7f, 0, 0x7f7f7f7f);
;             }
;             if (n == 0) {
; #pragma unroll
	ds_write_b128 v161, v[134:137] offset:13728
	v_mov_b32_e32 v232, s3
	v_mov_b32_e32 v235, s2
	v_cndmask_b32_e64 v232, v232, v235, s[4:5]
	v_lshl_or_b32 v232, v232, 9, v1
	global_load_dwordx4 v[134:137], v232, s[0:1]
	v_readlane_b32 s2, v154, 28
	v_readlane_b32 s3, v154, 29
	s_waitcnt vmcnt(33)
	ds_write_b128 v161, v[138:141] offset:14784
	v_mov_b32_e32 v233, s3
	v_mov_b32_e32 v235, s2
	v_cndmask_b32_e64 v233, v233, v235, s[4:5]
	v_lshl_or_b32 v233, v233, 9, v1
	global_load_dwordx4 v[138:141], v233, s[0:1]
	v_readlane_b32 s2, v154, 30
	v_readlane_b32 s3, v154, 31
	s_waitcnt vmcnt(33)
	ds_write_b128 v161, v[142:145] offset:15840
	v_mov_b32_e32 v234, s3
	v_mov_b32_e32 v235, s2
	v_cndmask_b32_e64 v234, v234, v235, s[4:5]
	v_lshl_or_b32 v234, v234, 9, v1
	global_load_dwordx4 v[142:145], v234, s[0:1]
	ds_read_b128 v[176:179], v162
	ds_read_b128 v[188:191], v173 offset:16896
	ds_read_b128 v[192:195], v173 offset:16928
	ds_read_b128 v[180:183], v162 offset:32
	ds_read_b128 v[196:199], v173 offset:16960
	ds_read_b128 v[200:203], v173 offset:16992
	ds_read_b128 v[236:239], v162 offset:64
	ds_read_b128 v[240:243], v173 offset:17024
	ds_read_b128 v[244:247], v173 offset:17056
	s_waitcnt lgkmcnt(6)
	v_mfma_scale_f32_32x32x64_f8f6f4 v[2:17], v[176:179], v[188:195], 0, v159, v159 op_sel_hi:[0,0,0] cbsz:4
	ds_read_b128 v[176:179], v162 offset:96
	ds_read_b128 v[188:191], v173 offset:17088
	ds_read_b128 v[192:195], v173 offset:17120
	s_waitcnt lgkmcnt(6)
	v_mfma_scale_f32_32x32x64_f8f6f4 v[2:17], v[180:183], v[196:203], v[2:17], v159, v159 op_sel_hi:[0,0,0] cbsz:4
	ds_read_b128 v[180:183], v162 offset:128
	ds_read_b128 v[196:199], v173 offset:17152
	ds_read_b128 v[200:203], v173 offset:17184
	s_waitcnt lgkmcnt(6)
	v_mfma_scale_f32_32x32x64_f8f6f4 v[2:17], v[236:239], v[240:247], v[2:17], v159, v159 op_sel_hi:[0,0,0] cbsz:4
	ds_read_b128 v[236:239], v162 offset:160
	ds_read_b128 v[240:243], v173 offset:17216
	ds_read_b128 v[244:247], v173 offset:17248
	s_waitcnt lgkmcnt(6)
	v_mfma_scale_f32_32x32x64_f8f6f4 v[2:17], v[176:179], v[188:195], v[2:17], v159, v159 op_sel_hi:[0,0,0] cbsz:4
	ds_read_b128 v[176:179], v162 offset:192
	ds_read_b128 v[188:191], v173 offset:17280
	ds_read_b128 v[192:195], v173 offset:17312
	s_waitcnt lgkmcnt(6)
	v_mfma_scale_f32_32x32x64_f8f6f4 v[2:17], v[180:183], v[196:203], v[2:17], v159, v159 op_sel_hi:[0,0,0] cbsz:4
	ds_read_b128 v[180:183], v162 offset:224
	ds_read_b128 v[196:199], v173 offset:17344
	ds_read_b128 v[200:203], v173 offset:17376
	s_waitcnt lgkmcnt(6)
	v_mfma_scale_f32_32x32x64_f8f6f4 v[2:17], v[236:239], v[240:247], v[2:17], v159, v159 op_sel_hi:[0,0,0] cbsz:4
	ds_read_b128 v[236:239], v157
	ds_read_b128 v[240:243], v173 offset:17408
	ds_read_b128 v[244:247], v173 offset:17440
	s_waitcnt lgkmcnt(6)
	v_mfma_scale_f32_32x32x64_f8f6f4 v[2:17], v[176:179], v[188:195], v[2:17], v159, v159 op_sel_hi:[0,0,0] cbsz:4
	ds_read_b128 v[176:179], v157 offset:32
	ds_read_b128 v[188:191], v173 offset:17472
	ds_read_b128 v[192:195], v173 offset:17504
	s_waitcnt lgkmcnt(6)
	v_mfma_scale_f32_32x32x64_f8f6f4 v[2:17], v[180:183], v[196:203], v[2:17], v159, v159 op_sel_hi:[0,0,0] cbsz:4
	ds_read_b128 v[180:183], v157 offset:64
	ds_read_b128 v[196:199], v173 offset:17536
	ds_read_b128 v[200:203], v173 offset:17568
	s_waitcnt lgkmcnt(6)
	v_mfma_scale_f32_32x32x64_f8f6f4 v[2:17], v[236:239], v[240:247], v[2:17], v159, v159 op_sel_hi:[0,0,0] cbsz:4
	ds_read_b128 v[236:239], v157 offset:96
	ds_read_b128 v[240:243], v173 offset:17600
	ds_read_b128 v[244:247], v173 offset:17632
	s_waitcnt lgkmcnt(6)
	v_mfma_scale_f32_32x32x64_f8f6f4 v[2:17], v[176:179], v[188:195], v[2:17], v159, v159 op_sel_hi:[0,0,0] cbsz:4
	ds_read_b128 v[176:179], v157 offset:128
	ds_read_b128 v[188:191], v173 offset:17664
	ds_read_b128 v[192:195], v173 offset:17696
	s_waitcnt lgkmcnt(6)
	v_mfma_scale_f32_32x32x64_f8f6f4 v[2:17], v[180:183], v[196:203], v[2:17], v159, v159 op_sel_hi:[0,0,0] cbsz:4
	ds_read_b128 v[180:183], v157 offset:160
	ds_read_b128 v[196:199], v173 offset:17728
	ds_read_b128 v[200:203], v173 offset:17760
	s_waitcnt lgkmcnt(6)
	v_mfma_scale_f32_32x32x64_f8f6f4 v[2:17], v[236:239], v[240:247], v[2:17], v159, v159 op_sel_hi:[0,0,0] cbsz:4
	ds_read_b128 v[236:239], v157 offset:192
	ds_read_b128 v[240:243], v173 offset:17792
	ds_read_b128 v[244:247], v173 offset:17824
	s_waitcnt lgkmcnt(6)
	v_mfma_scale_f32_32x32x64_f8f6f4 v[2:17], v[176:179], v[188:195], v[2:17], v159, v159 op_sel_hi:[0,0,0] cbsz:4
	ds_read_b128 v[176:179], v157 offset:224
	ds_read_b128 v[188:191], v173 offset:17856
	ds_read_b128 v[192:195], v173 offset:17888
	s_waitcnt lgkmcnt(6)
	v_mfma_scale_f32_32x32x64_f8f6f4 v[2:17], v[180:183], v[196:203], v[2:17], v159, v159 op_sel_hi:[0,0,0] cbsz:4
	s_waitcnt lgkmcnt(3)
	v_mfma_scale_f32_32x32x64_f8f6f4 v[2:17], v[236:239], v[240:247], v[2:17], v159, v159 op_sel_hi:[0,0,0] cbsz:4
	s_waitcnt lgkmcnt(0)
	v_mfma_scale_f32_32x32x64_f8f6f4 v[2:17], v[176:179], v[188:195], v[2:17], v159, v159 op_sel_hi:[0,0,0] cbsz:4
	s_and_saveexec_b64 s[2:3], s[6:7]
	s_cbranch_execz .Lud8_g0
	s_nop 15
	s_nop 0
	ds_write_b128 v173, v[2:5] offset:17920
	ds_write_b128 v173, v[6:9] offset:17952
	ds_write_b128 v173, v[10:13] offset:17984
	ds_write_b128 v173, v[14:17] offset:18016
; #define GAS __attribute__((address_space(1)))
; #define LAS __attribute__((address_space(3)))
; #define ULOADA(slot, ereg, lb, j_) { const int ea_ = __builtin_amdgcn_readlane((ereg), (lb) + 2 * (j_)), eb_ = __builtin_amdgcn_readlane((ereg), (lb) + 2 * (j_) + 1); const int el_ = hh ? eb_ : ea_; \
;         ring[slot] = *(const GAS v4u*)(U4 + (((unsigned)el_ << 9) + laneoff)); }
; __device__ __forceinline__ void phase_gather_u_mfma(LAS unsigned char* lds, const bf16* X, const int* EID, float* GATE, const unsigned char* U4, const float* DQU, const float* DQV) {
;     ...
;         const int tn = t + NGW; const bool has_next = tn < T;
;         int ne0 = e0, ne1 = e1;
;         if (has_next) { ne0 = EID[(size_t)tn * 128 + lane]; ne1 = EID[(size_t)tn * 128 + 64 + lane]; }
;         const float gt0 = GATE[(size_t)t * 128 + lane], gt1 = GATE[(size_t)t * 128 + 64 + lane];
;         const float dqu0 = DQU[e0], dqu1 = DQU[e1], dqv0 = DQV[e0], dqv1 = DQV[e1];
;         { const v4u xa = *((const GAS v4u*)(X + (size_t)t * D) + 2 * lane), xb = *((const GAS v4u*)(X + (size_t)t * D) + 2 * lane + 1);
;     ...
;         for (int q = 0; q < 4; ++q) {
; #pragma unroll
;             for (int j = 0; j < 16; ++j) *(LAS v4u*)(rows + hh * 528 + 16 * n + j * 1056) = ring[j];
;             __builtin_amdgcn_sched_barrier(0);
;             { const int qn = q + 1;
;               const int er = (qn >= 4) ? ne0 : ((qn >> 1) ? e1 : e0); const int lb = (qn >= 4) ? 0 : 32 * (qn & 1);
; #pragma unroll
;               for (int j = 0; j < 16; ++j) ULOADA(j, er, lb, j) }
.Lud8_g0:
	s_or_b64 exec, exec, s[2:3]
	s_nop 15
	ds_read_b32 v174, v163 offset:17920
	v_readlane_b32 s2, v154, 32
	v_readlane_b32 s3, v154, 33
	s_waitcnt vmcnt(33)
	ds_write_b128 v161, v[18:21]
	v_mov_b32_e32 v248, s3
	v_mov_b32_e32 v235, s2
	v_cndmask_b32_e64 v248, v248, v235, s[4:5]
	v_lshl_or_b32 v248, v248, 9, v1
	global_load_dwordx4 v[18:21], v248, s[0:1]
	v_readlane_b32 s2, v154, 34
	v_readlane_b32 s3, v154, 35
	s_waitcnt vmcnt(33)
	ds_write_b128 v161, v[22:25] offset:1056
	v_mov_b32_e32 v249, s3
	v_mov_b32_e32 v235, s2
	v_cndmask_b32_e64 v249, v249, v235, s[4:5]
	v_lshl_or_b32 v249, v249, 9, v1
	global_load_dwordx4 v[22:25], v249, s[0:1]
	v_readlane_b32 s2, v154, 36
	v_readlane_b32 s3, v154, 37
	s_waitcnt vmcnt(33)
	ds_write_b128 v161, v[26:29] offset:2112
	v_mov_b32_e32 v250, s3
	v_mov_b32_e32 v235, s2
	v_cndmask_b32_e64 v250, v250, v235, s[4:5]
	v_lshl_or_b32 v250, v250, 9, v1
	global_load_dwordx4 v[26:29], v250, s[0:1]
	v_readlane_b32 s2, v154, 38
	v_readlane_b32 s3, v154, 39
	s_waitcnt vmcnt(33)
	ds_write_b128 v161, v[30:33] offset:3168
	v_mov_b32_e32 v251, s3
	v_mov_b32_e32 v235, s2
	v_cndmask_b32_e64 v251, v251, v235, s[4:5]
	v_lshl_or_b32 v251, v251, 9, v1
	global_load_dwordx4 v[30:33], v251, s[0:1]
	v_readlane_b32 s2, v154, 40
	v_readlane_b32 s3, v154, 41
	s_waitcnt vmcnt(33)
	ds_write_b128 v161, v[34:37] offset:4224
	v_mov_b32_e32 v252, s3
	v_mov_b32_e32 v235, s2
	v_cndmask_b32_e64 v252, v252, v235, s[4:5]
	v_lshl_or_b32 v252, v252, 9, v1
	global_load_dwordx4 v[34:37], v252, s[0:1]
	v_readlane_b32 s2, v154, 42
	v_readlane_b32 s3, v154, 43
	s_waitcnt vmcnt(33)
	ds_write_b128 v161, v[38:41] offset:5280
	v_mov_b32_e32 v253, s3
	v_mov_b32_e32 v235, s2
	v_cndmask_b32_e64 v253, v253, v235, s[4:5]
	v_lshl_or_b32 v253, v253, 9, v1
	global_load_dwordx4 v[38:41], v253, s[0:1]
	v_readlane_b32 s2, v154, 44
	v_readlane_b32 s3, v154, 45
	s_waitcnt vmcnt(33)
	ds_write_b128 v161, v[42:45] offset:6336
	v_mov_b32_e32 v254, s3
	v_mov_b32_e32 v235, s2
	v_cndmask_b32_e64 v254, v254, v235, s[4:5]
	v_lshl_or_b32 v254, v254, 9, v1
	global_load_dwordx4 v[42:45], v254, s[0:1]
	v_readlane_b32 s2, v154, 46
	v_readlane_b32 s3, v154, 47
	s_waitcnt vmcnt(33)
	ds_write_b128 v161, v[46:49] offset:7392
	v_mov_b32_e32 v204, s3
	v_mov_b32_e32 v235, s2
	v_cndmask_b32_e64 v204, v204, v235, s[4:5]
	v_lshl_or_b32 v204, v204, 9, v1
	global_load_dwordx4 v[46:49], v204, s[0:1]
	v_readlane_b32 s2, v154, 48
	v_readlane_b32 s3, v154, 49
	s_waitcnt vmcnt(33)
	ds_write_b128 v161, v[50:53] offset:8448
	v_mov_b32_e32 v205, s3
	v_mov_b32_e32 v235, s2
	v_cndmask_b32_e64 v205, v205, v235, s[4:5]
	v_lshl_or_b32 v205, v205, 9, v1
	global_load_dwordx4 v[50:53], v205, s[0:1]
	v_readlane_b32 s2, v154, 50
	v_readlane_b32 s3, v154, 51
	s_waitcnt vmcnt(33)
	ds_write_b128 v161, v[54:57] offset:9504
	v_mov_b32_e32 v206, s3
	v_mov_b32_e32 v235, s2
	v_cndmask_b32_e64 v206, v206, v235, s[4:5]
	v_lshl_or_b32 v206, v206, 9, v1
	global_load_dwordx4 v[54:57], v206, s[0:1]
	v_readlane_b32 s2, v154, 52
	v_readlane_b32 s3, v154, 53
	s_waitcnt vmcnt(33)
	ds_write_b128 v161, v[58:61] offset:10560
	v_mov_b32_e32 v207, s3
	v_mov_b32_e32 v235, s2
	v_cndmask_b32_e64 v207, v207, v235, s[4:5]
	v_lshl_or_b32 v207, v207, 9, v1
	global_load_dwordx4 v[58:61], v207, s[0:1]
	v_readlane_b32 s2, v154, 54
	v_readlane_b32 s3, v154, 55
	s_waitcnt vmcnt(33)
	ds_write_b128 v161, v[62:65] offset:11616
	v_mov_b32_e32 v230, s3
	v_mov_b32_e32 v235, s2
	v_cndmask_b32_e64 v230, v230, v235, s[4:5]
	v_lshl_or_b32 v230, v230, 9, v1
	global_load_dwordx4 v[62:65], v230, s[0:1]
	v_readlane_b32 s2, v154, 56
	v_readlane_b32 s3, v154, 57
	s_waitcnt vmcnt(33)
	ds_write_b128 v161, v[66:69] offset:12672
	v_mov_b32_e32 v231, s3
	v_mov_b32_e32 v235, s2
	v_cndmask_b32_e64 v231, v231, v235, s[4:5]
	v_lshl_or_b32 v231, v231, 9, v1
	global_load_dwordx4 v[66:69], v231, s[0:1]
	v_readlane_b32 s2, v154, 58
	v_readlane_b32 s3, v154, 59
	s_waitcnt vmcnt(33)
	ds_write_b128 v161, v[70:73] offset:13728
	v_mov_b32_e32 v232, s3
	v_mov_b32_e32 v235, s2
	v_cndmask_b32_e64 v232, v232, v235, s[4:5]
	v_lshl_or_b32 v232, v232, 9, v1
	global_load_dwordx4 v[70:73], v232, s[0:1]
	v_readlane_b32 s2, v154, 60
	v_readlane_b32 s3, v154, 61
	s_waitcnt vmcnt(33)
	ds_write_b128 v161, v[74:77] offset:14784
	v_mov_b32_e32 v233, s3
	v_mov_b32_e32 v235, s2
	v_cndmask_b32_e64 v233, v233, v235, s[4:5]
	v_lshl_or_b32 v233, v233, 9, v1
	global_load_dwordx4 v[74:77], v233, s[0:1]
	v_readlane_b32 s2, v154, 62
	v_readlane_b32 s3, v154, 63
	s_waitcnt vmcnt(33)
	ds_write_b128 v161, v[78:81] offset:15840
	v_mov_b32_e32 v234, s3
	v_mov_b32_e32 v235, s2
	v_cndmask_b32_e64 v234, v234, v235, s[4:5]
	v_lshl_or_b32 v234, v234, 9, v1
	global_load_dwordx4 v[78:81], v234, s[0:1]
	s_waitcnt vmcnt(32)
	s_cmpk_gt_i32 s14, 0x7fff
	s_cselect_b32 s15, s18, s14
	s_ashr_i32 s3, s15, 31
	s_mov_b32 s2, s15
	s_lshl_b64 s[2:3], s[2:3], 11
	v_lshl_add_u64 v[228:229], v[150:151], 0, s[2:3]
	global_load_dwordx4 v[212:215], v[228:229], off nt
	global_load_dwordx4 v[216:219], v[228:229], off offset:16 nt
	s_ashr_i32 s3, s15, 31
	s_mov_b32 s2, s15
	s_lshl_b64 s[2:3], s[2:3], 9
	v_lshl_add_u64 v[228:229], v[148:149], 0, s[2:3]
	global_load_dword v220, v[228:229], off nt
	global_load_dword v221, v[228:229], off offset:256 nt
	v_mov_b32_e32 v228, v166
	v_ashrrev_i32_e32 v229, 31, v166
	v_lshlrev_b64 v[228:229], 3, v[228:229]
	v_lshl_add_u64 v[228:229], s[10:11], 0, v[228:229]
	global_load_dwordx2 v[222:223], v[228:229], off
	v_mov_b32_e32 v228, v167
	v_ashrrev_i32_e32 v229, 31, v167
	v_lshlrev_b64 v[228:229], 3, v[228:229]
	v_lshl_add_u64 v[228:229], s[10:11], 0, v[228:229]
	global_load_dwordx2 v[224:225], v[228:229], off
	ds_read_b128 v[176:179], v162
	ds_read_b128 v[188:191], v173 offset:16896
	ds_read_b128 v[192:195], v173 offset:16928
	ds_read_b128 v[180:183], v162 offset:32
	ds_read_b128 v[196:199], v173 offset:16960
	ds_read_b128 v[200:203], v173 offset:16992
	ds_read_b128 v[236:239], v162 offset:64
	ds_read_b128 v[240:243], v173 offset:17024
	ds_read_b128 v[244:247], v173 offset:17056
	s_waitcnt lgkmcnt(6)
; #define LAS __attribute__((address_space(3)))
; __device__ __forceinline__ void phase_gather_u_mfma(LAS unsigned char* lds, const bf16* X, const int* EID, float* GATE, const unsigned char* U4, const float* DQU, const float* DQV) {
;     ...
;         for (int q = 0; q < 4; ++q) {
; #pragma unroll
;             for (int j = 0; j < 16; ++j) *(LAS v4u*)(rows + hh * 528 + 16 * n + j * 1056) = ring[j];
;             __builtin_amdgcn_sched_barrier(0);
;             { const int qn = q + 1;
;     ...
;             f32x16 acc;
; #pragma unroll
;             for (int r = 0; r < 16; ++r) acc[r] = 0.f;
; #pragma unroll
;             for (int ks = 0; ks < 8; ++ks) {
;                 const v4u a4 = *(const LAS v4u*)(rows + n * 528 + 16 * hh + 32 * ks);
;                 v8i A, B;
;                 A[0] = (int)a4.x; A[1] = (int)a4.y; A[2] = (int)a4.z; A[3] = (int)a4.w; A[4] = 0; A[5] = 0; A[6] = 0; A[7] = 0;
;                 B[0] = (int)xf0[ks].x; B[1] = (int)xf0[ks].y; B[2] = (int)xf0[ks].z; B[3] = (int)xf0[ks].w; B[4] = (int)xf1[ks].x; B[5] = (int)xf1[ks].y; B[6] = (int)xf1[ks].z; B[7] = (int)xf1[ks].w;
;                 acc = __builtin_amdgcn_mfma_scale_f32_32x32x64_f8f6f4(A, B, acc, 4, 0, 0, 0x7f7f7f7f, 0, 0x7f7f7f7f);
;                 if ((ks & 1) == 1) __builtin_amdgcn_sched_barrier(0);
;             }
;             unsigned xo = 16u * (unsigned)hh; asm volatile("" : "+v"(xo));
; #pragma unroll 2
;             for (int ks = 8; ks < 16; ++ks) {
;                 const v4u a4 = *(const LAS v4u*)(rows + n * 528 + 16 * hh + 32 * ks);
;                 const v4u b0 = *(const LAS v4u*)(x8 + xo + 64 * ks), b1 = *(const LAS v4u*)(x8 + xo + 64 * ks + 32);
;                 v8i A, B;
;                 A[0] = (int)a4.x; A[1] = (int)a4.y; A[2] = (int)a4.z; A[3] = (int)a4.w; A[4] = 0; A[5] = 0; A[6] = 0; A[7] = 0;
;                 B[0] = (int)b0.x; B[1] = (int)b0.y; B[2] = (int)b0.z; B[3] = (int)b0.w; B[4] = (int)b1.x; B[5] = (int)b1.y; B[6] = (int)b1.z; B[7] = (int)b1.w;
;                 acc = __builtin_amdgcn_mfma_scale_f32_32x32x64_f8f6f4(A, B, acc, 4, 0, 0, 0x7f7f7f7f, 0, 0x7f7f7f7f);
;             }
;             if (n == 0) {
; #pragma unroll
;                 for (int r = 0; r < 16; ++r) { const float av = acc[r]; *(LAS float*)(x8 + 1024 + 4 * ((r & 3) + 8 * (r >> 2) + 4 * hh)) = av; }
;             }
;             const float act = *(const LAS float*)(x8 + 1024 + 4 * n);
	v_mfma_scale_f32_32x32x64_f8f6f4 v[2:17], v[176:179], v[188:195], 0, v159, v159 op_sel_hi:[0,0,0] cbsz:4
	ds_read_b128 v[176:179], v162 offset:96
	ds_read_b128 v[188:191], v173 offset:17088
	ds_read_b128 v[192:195], v173 offset:17120
	s_waitcnt lgkmcnt(6)
	v_mfma_scale_f32_32x32x64_f8f6f4 v[2:17], v[180:183], v[196:203], v[2:17], v159, v159 op_sel_hi:[0,0,0] cbsz:4
	ds_read_b128 v[180:183], v162 offset:128
	ds_read_b128 v[196:199], v173 offset:17152
	ds_read_b128 v[200:203], v173 offset:17184
	s_waitcnt lgkmcnt(6)
	v_mfma_scale_f32_32x32x64_f8f6f4 v[2:17], v[236:239], v[240:247], v[2:17], v159, v159 op_sel_hi:[0,0,0] cbsz:4
	ds_read_b128 v[236:239], v162 offset:160
	ds_read_b128 v[240:243], v173 offset:17216
	ds_read_b128 v[244:247], v173 offset:17248
	s_waitcnt lgkmcnt(6)
	v_mfma_scale_f32_32x32x64_f8f6f4 v[2:17], v[176:179], v[188:195], v[2:17], v159, v159 op_sel_hi:[0,0,0] cbsz:4
	ds_read_b128 v[176:179], v162 offset:192
	ds_read_b128 v[188:191], v173 offset:17280
	ds_read_b128 v[192:195], v173 offset:17312
	s_waitcnt lgkmcnt(6)
	v_mfma_scale_f32_32x32x64_f8f6f4 v[2:17], v[180:183], v[196:203], v[2:17], v159, v159 op_sel_hi:[0,0,0] cbsz:4
	ds_read_b128 v[180:183], v162 offset:224
	ds_read_b128 v[196:199], v173 offset:17344
	ds_read_b128 v[200:203], v173 offset:17376
	s_waitcnt lgkmcnt(6)
	v_mfma_scale_f32_32x32x64_f8f6f4 v[2:17], v[236:239], v[240:247], v[2:17], v159, v159 op_sel_hi:[0,0,0] cbsz:4
	ds_read_b128 v[236:239], v157
	ds_read_b128 v[240:243], v173 offset:17408
	ds_read_b128 v[244:247], v173 offset:17440
	s_waitcnt lgkmcnt(6)
	v_mfma_scale_f32_32x32x64_f8f6f4 v[2:17], v[176:179], v[188:195], v[2:17], v159, v159 op_sel_hi:[0,0,0] cbsz:4
	ds_read_b128 v[176:179], v157 offset:32
	ds_read_b128 v[188:191], v173 offset:17472
	ds_read_b128 v[192:195], v173 offset:17504
	s_waitcnt lgkmcnt(6)
	v_mfma_scale_f32_32x32x64_f8f6f4 v[2:17], v[180:183], v[196:203], v[2:17], v159, v159 op_sel_hi:[0,0,0] cbsz:4
	ds_read_b128 v[180:183], v157 offset:64
	ds_read_b128 v[196:199], v173 offset:17536
	ds_read_b128 v[200:203], v173 offset:17568
	s_waitcnt lgkmcnt(6)
	v_mfma_scale_f32_32x32x64_f8f6f4 v[2:17], v[236:239], v[240:247], v[2:17], v159, v159 op_sel_hi:[0,0,0] cbsz:4
	ds_read_b128 v[236:239], v157 offset:96
	ds_read_b128 v[240:243], v173 offset:17600
	ds_read_b128 v[244:247], v173 offset:17632
	s_waitcnt lgkmcnt(6)
	v_mfma_scale_f32_32x32x64_f8f6f4 v[2:17], v[176:179], v[188:195], v[2:17], v159, v159 op_sel_hi:[0,0,0] cbsz:4
	ds_read_b128 v[176:179], v157 offset:128
	ds_read_b128 v[188:191], v173 offset:17664
	ds_read_b128 v[192:195], v173 offset:17696
	s_waitcnt lgkmcnt(6)
	v_mfma_scale_f32_32x32x64_f8f6f4 v[2:17], v[180:183], v[196:203], v[2:17], v159, v159 op_sel_hi:[0,0,0] cbsz:4
	ds_read_b128 v[180:183], v157 offset:160
	ds_read_b128 v[196:199], v173 offset:17728
	ds_read_b128 v[200:203], v173 offset:17760
	s_waitcnt lgkmcnt(6)
	v_mfma_scale_f32_32x32x64_f8f6f4 v[2:17], v[236:239], v[240:247], v[2:17], v159, v159 op_sel_hi:[0,0,0] cbsz:4
	ds_read_b128 v[236:239], v157 offset:192
	ds_read_b128 v[240:243], v173 offset:17792
	ds_read_b128 v[244:247], v173 offset:17824
	s_waitcnt lgkmcnt(6)
	v_mfma_scale_f32_32x32x64_f8f6f4 v[2:17], v[176:179], v[188:195], v[2:17], v159, v159 op_sel_hi:[0,0,0] cbsz:4
	ds_read_b128 v[176:179], v157 offset:224
	ds_read_b128 v[188:191], v173 offset:17856
	ds_read_b128 v[192:195], v173 offset:17888
	s_waitcnt lgkmcnt(6)
	v_mfma_scale_f32_32x32x64_f8f6f4 v[2:17], v[180:183], v[196:203], v[2:17], v159, v159 op_sel_hi:[0,0,0] cbsz:4
	s_waitcnt lgkmcnt(3)
	v_mfma_scale_f32_32x32x64_f8f6f4 v[2:17], v[236:239], v[240:247], v[2:17], v159, v159 op_sel_hi:[0,0,0] cbsz:4
	s_waitcnt lgkmcnt(0)
	v_mfma_scale_f32_32x32x64_f8f6f4 v[2:17], v[176:179], v[188:195], v[2:17], v159, v159 op_sel_hi:[0,0,0] cbsz:4
	s_and_saveexec_b64 s[2:3], s[6:7]
	s_cbranch_execz .Lud8_g1
	s_nop 15
	s_nop 0
	ds_write_b128 v173, v[2:5] offset:17920
	ds_write_b128 v173, v[6:9] offset:17952
	ds_write_b128 v173, v[10:13] offset:17984
	ds_write_b128 v173, v[14:17] offset:18016
.Lud8_g1:
	s_or_b64 exec, exec, s[2:3]
	s_nop 15
	ds_read_b32 v175, v163 offset:17920
	v_readlane_b32 s2, v166, 0
	v_readlane_b32 s3, v166, 1
	s_waitcnt vmcnt(37)
	ds_write_b128 v161, v[82:85]
	v_mov_b32_e32 v248, s3
	v_mov_b32_e32 v235, s2
	v_cndmask_b32_e64 v248, v248, v235, s[4:5]
	v_lshl_or_b32 v248, v248, 9, v1
	global_load_dwordx4 v[82:85], v248, s[0:1]
	v_readlane_b32 s2, v166, 2
	v_readlane_b32 s3, v166, 3
	s_waitcnt vmcnt(37)
	ds_write_b128 v161, v[86:89] offset:1056
	v_mov_b32_e32 v249, s3
	v_mov_b32_e32 v235, s2
	v_cndmask_b32_e64 v249, v249, v235, s[4:5]
	v_lshl_or_b32 v249, v249, 9, v1
	global_load_dwordx4 v[86:89], v249, s[0:1]
	v_readlane_b32 s2, v166, 4
	v_readlane_b32 s3, v166, 5
	s_waitcnt vmcnt(37)
	ds_write_b128 v161, v[90:93] offset:2112
	v_mov_b32_e32 v250, s3
	v_mov_b32_e32 v235, s2
	v_cndmask_b32_e64 v250, v250, v235, s[4:5]
	v_lshl_or_b32 v250, v250, 9, v1
	global_load_dwordx4 v[90:93], v250, s[0:1]
	v_readlane_b32 s2, v166, 6
	v_readlane_b32 s3, v166, 7
	s_waitcnt vmcnt(37)
	ds_write_b128 v161, v[94:97] offset:3168
	v_mov_b32_e32 v251, s3
	v_mov_b32_e32 v235, s2
	v_cndmask_b32_e64 v251, v251, v235, s[4:5]
	v_lshl_or_b32 v251, v251, 9, v1
	global_load_dwordx4 v[94:97], v251, s[0:1]
	v_readlane_b32 s2, v166, 8
	v_readlane_b32 s3, v166, 9
	s_waitcnt vmcnt(37)
	ds_write_b128 v161, v[98:101] offset:4224
	v_mov_b32_e32 v252, s3
	v_mov_b32_e32 v235, s2
	v_cndmask_b32_e64 v252, v252, v235, s[4:5]
	v_lshl_or_b32 v252, v252, 9, v1
	global_load_dwordx4 v[98:101], v252, s[0:1]
	v_readlane_b32 s2, v166, 10
	v_readlane_b32 s3, v166, 11
	s_waitcnt vmcnt(37)
; #define LAS __attribute__((address_space(3)))
; __device__ __forceinline__ void phase_gather_u_mfma(LAS unsigned char* lds, const bf16* X, const int* EID, float* GATE, const unsigned char* U4, const float* DQU, const float* DQV) {
;     ...
;         for (int q = 0; q < 4; ++q) {
; #pragma unroll
;             for (int j = 0; j < 16; ++j) *(LAS v4u*)(rows + hh * 528 + 16 * n + j * 1056) = ring[j];
;             __builtin_amdgcn_sched_barrier(0);
;             { const int qn = q + 1;
;               const int er = (qn >= 4) ? ne0 : ((qn >> 1) ? e1 : e0); const int lb = (qn >= 4) ? 0 : 32 * (qn & 1);
; #pragma unroll
;               for (int j = 0; j < 16; ++j) ULOADA(j, er, lb, j) }
;             __builtin_amdgcn_sched_barrier(0);
;             f32x16 acc;
; #pragma unroll
;             for (int r = 0; r < 16; ++r) acc[r] = 0.f;
; #pragma unroll
;             for (int ks = 0; ks < 8; ++ks) {
;                 const v4u a4 = *(const LAS v4u*)(rows + n * 528 + 16 * hh + 32 * ks);
;                 v8i A, B;
;                 A[0] = (int)a4.x; A[1] = (int)a4.y; A[2] = (int)a4.z; A[3] = (int)a4.w; A[4] = 0; A[5] = 0; A[6] = 0; A[7] = 0;
;                 B[0] = (int)xf0[ks].x; B[1] = (int)xf0[ks].y; B[2] = (int)xf0[ks].z; B[3] = (int)xf0[ks].w; B[4] = (int)xf1[ks].x; B[5] = (int)xf1[ks].y; B[6] = (int)xf1[ks].z; B[7] = (int)xf1[ks].w;
;                 acc = __builtin_amdgcn_mfma_scale_f32_32x32x64_f8f6f4(A, B, acc, 4, 0, 0, 0x7f7f7f7f, 0, 0x7f7f7f7f);
;                 if ((ks & 1) == 1) __builtin_amdgcn_sched_barrier(0);
;             }
;             unsigned xo = 16u * (unsigned)hh; asm volatile("" : "+v"(xo));
; #pragma unroll 2
;             for (int ks = 8; ks < 16; ++ks) {
;                 const v4u a4 = *(const LAS v4u*)(rows + n * 528 + 16 * hh + 32 * ks);
;                 const v4u b0 = *(const LAS v4u*)(x8 + xo + 64 * ks), b1 = *(const LAS v4u*)(x8 + xo + 64 * ks + 32);
;                 v8i A, B;
;                 A[0] = (int)a4.x; A[1] = (int)a4.y; A[2] = (int)a4.z; A[3] = (int)a4.w; A[4] = 0; A[5] = 0; A[6] = 0; A[7] = 0;
;                 B[0] = (int)b0.x; B[1] = (int)b0.y; B[2] = (int)b0.z; B[3] = (int)b0.w; B[4] = (int)b1.x; B[5] = (int)b1.y; B[6] = (int)b1.z; B[7] = (int)b1.w;
;                 acc = __builtin_amdgcn_mfma_scale_f32_32x32x64_f8f6f4(A, B, acc, 4, 0, 0, 0x7f7f7f7f, 0, 0x7f7f7f7f);
;             }
	ds_write_b128 v161, v[102:105] offset:5280
	v_mov_b32_e32 v253, s3
	v_mov_b32_e32 v235, s2
	v_cndmask_b32_e64 v253, v253, v235, s[4:5]
	v_lshl_or_b32 v253, v253, 9, v1
	global_load_dwordx4 v[102:105], v253, s[0:1]
	v_readlane_b32 s2, v166, 12
	v_readlane_b32 s3, v166, 13
	s_waitcnt vmcnt(37)
	ds_write_b128 v161, v[106:109] offset:6336
	v_mov_b32_e32 v254, s3
	v_mov_b32_e32 v235, s2
	v_cndmask_b32_e64 v254, v254, v235, s[4:5]
	v_lshl_or_b32 v254, v254, 9, v1
	global_load_dwordx4 v[106:109], v254, s[0:1]
	v_readlane_b32 s2, v166, 14
	v_readlane_b32 s3, v166, 15
	s_waitcnt vmcnt(37)
	ds_write_b128 v161, v[110:113] offset:7392
	v_mov_b32_e32 v204, s3
	v_mov_b32_e32 v235, s2
	v_cndmask_b32_e64 v204, v204, v235, s[4:5]
	v_lshl_or_b32 v204, v204, 9, v1
	global_load_dwordx4 v[110:113], v204, s[0:1]
	v_readlane_b32 s2, v166, 16
	v_readlane_b32 s3, v166, 17
	s_waitcnt vmcnt(37)
	ds_write_b128 v161, v[114:117] offset:8448
	v_mov_b32_e32 v205, s3
	v_mov_b32_e32 v235, s2
	v_cndmask_b32_e64 v205, v205, v235, s[4:5]
	v_lshl_or_b32 v205, v205, 9, v1
	global_load_dwordx4 v[114:117], v205, s[0:1]
	v_readlane_b32 s2, v166, 18
	v_readlane_b32 s3, v166, 19
	s_waitcnt vmcnt(37)
	ds_write_b128 v161, v[118:121] offset:9504
	v_mov_b32_e32 v206, s3
	v_mov_b32_e32 v235, s2
	v_cndmask_b32_e64 v206, v206, v235, s[4:5]
	v_lshl_or_b32 v206, v206, 9, v1
	global_load_dwordx4 v[118:121], v206, s[0:1]
	v_readlane_b32 s2, v166, 20
	v_readlane_b32 s3, v166, 21
	s_waitcnt vmcnt(37)
	ds_write_b128 v161, v[122:125] offset:10560
	v_mov_b32_e32 v207, s3
	v_mov_b32_e32 v235, s2
	v_cndmask_b32_e64 v207, v207, v235, s[4:5]
	v_lshl_or_b32 v207, v207, 9, v1
	global_load_dwordx4 v[122:125], v207, s[0:1]
	v_readlane_b32 s2, v166, 22
	v_readlane_b32 s3, v166, 23
	s_waitcnt vmcnt(37)
	ds_write_b128 v161, v[126:129] offset:11616
	v_mov_b32_e32 v230, s3
	v_mov_b32_e32 v235, s2
	v_cndmask_b32_e64 v230, v230, v235, s[4:5]
	v_lshl_or_b32 v230, v230, 9, v1
	global_load_dwordx4 v[126:129], v230, s[0:1]
	v_readlane_b32 s2, v166, 24
	v_readlane_b32 s3, v166, 25
	s_waitcnt vmcnt(37)
	ds_write_b128 v161, v[130:133] offset:12672
	v_mov_b32_e32 v231, s3
	v_mov_b32_e32 v235, s2
	v_cndmask_b32_e64 v231, v231, v235, s[4:5]
	v_lshl_or_b32 v231, v231, 9, v1
	global_load_dwordx4 v[130:133], v231, s[0:1]
	v_readlane_b32 s2, v166, 26
	v_readlane_b32 s3, v166, 27
	s_waitcnt vmcnt(37)
	ds_write_b128 v161, v[134:137] offset:13728
	v_mov_b32_e32 v232, s3
	v_mov_b32_e32 v235, s2
	v_cndmask_b32_e64 v232, v232, v235, s[4:5]
	v_lshl_or_b32 v232, v232, 9, v1
	global_load_dwordx4 v[134:137], v232, s[0:1]
	v_readlane_b32 s2, v166, 28
	v_readlane_b32 s3, v166, 29
	s_waitcnt vmcnt(37)
	ds_write_b128 v161, v[138:141] offset:14784
	v_mov_b32_e32 v233, s3
	v_mov_b32_e32 v235, s2
	v_cndmask_b32_e64 v233, v233, v235, s[4:5]
	v_lshl_or_b32 v233, v233, 9, v1
	global_load_dwordx4 v[138:141], v233, s[0:1]
	v_readlane_b32 s2, v166, 30
	v_readlane_b32 s3, v166, 31
	s_waitcnt vmcnt(37)
	ds_write_b128 v161, v[142:145] offset:15840
	v_mov_b32_e32 v234, s3
	v_mov_b32_e32 v235, s2
	v_cndmask_b32_e64 v234, v234, v235, s[4:5]
	v_lshl_or_b32 v234, v234, 9, v1
	global_load_dwordx4 v[142:145], v234, s[0:1]
	ds_read_b128 v[176:179], v162
	ds_read_b128 v[188:191], v173 offset:16896
	ds_read_b128 v[192:195], v173 offset:16928
	ds_read_b128 v[180:183], v162 offset:32
	ds_read_b128 v[196:199], v173 offset:16960
	ds_read_b128 v[200:203], v173 offset:16992
	ds_read_b128 v[236:239], v162 offset:64
	ds_read_b128 v[240:243], v173 offset:17024
	ds_read_b128 v[244:247], v173 offset:17056
	s_waitcnt lgkmcnt(6)
	v_mfma_scale_f32_32x32x64_f8f6f4 v[2:17], v[176:179], v[188:195], 0, v159, v159 op_sel_hi:[0,0,0] cbsz:4
	ds_read_b128 v[176:179], v162 offset:96
	ds_read_b128 v[188:191], v173 offset:17088
	ds_read_b128 v[192:195], v173 offset:17120
	s_waitcnt lgkmcnt(6)
	v_mfma_scale_f32_32x32x64_f8f6f4 v[2:17], v[180:183], v[196:203], v[2:17], v159, v159 op_sel_hi:[0,0,0] cbsz:4
	ds_read_b128 v[180:183], v162 offset:128
	ds_read_b128 v[196:199], v173 offset:17152
	ds_read_b128 v[200:203], v173 offset:17184
	s_waitcnt lgkmcnt(6)
	v_mfma_scale_f32_32x32x64_f8f6f4 v[2:17], v[236:239], v[240:247], v[2:17], v159, v159 op_sel_hi:[0,0,0] cbsz:4
	ds_read_b128 v[236:239], v162 offset:160
	ds_read_b128 v[240:243], v173 offset:17216
	ds_read_b128 v[244:247], v173 offset:17248
	s_waitcnt lgkmcnt(6)
	v_mfma_scale_f32_32x32x64_f8f6f4 v[2:17], v[176:179], v[188:195], v[2:17], v159, v159 op_sel_hi:[0,0,0] cbsz:4
	ds_read_b128 v[176:179], v162 offset:192
	ds_read_b128 v[188:191], v173 offset:17280
	ds_read_b128 v[192:195], v173 offset:17312
	s_waitcnt lgkmcnt(6)
	v_mfma_scale_f32_32x32x64_f8f6f4 v[2:17], v[180:183], v[196:203], v[2:17], v159, v159 op_sel_hi:[0,0,0] cbsz:4
	ds_read_b128 v[180:183], v162 offset:224
	ds_read_b128 v[196:199], v173 offset:17344
	ds_read_b128 v[200:203], v173 offset:17376
	s_waitcnt lgkmcnt(6)
	v_mfma_scale_f32_32x32x64_f8f6f4 v[2:17], v[236:239], v[240:247], v[2:17], v159, v159 op_sel_hi:[0,0,0] cbsz:4
	ds_read_b128 v[236:239], v157
	ds_read_b128 v[240:243], v173 offset:17408
	ds_read_b128 v[244:247], v173 offset:17440
	s_waitcnt lgkmcnt(6)
	v_mfma_scale_f32_32x32x64_f8f6f4 v[2:17], v[176:179], v[188:195], v[2:17], v159, v159 op_sel_hi:[0,0,0] cbsz:4
	ds_read_b128 v[176:179], v157 offset:32
	ds_read_b128 v[188:191], v173 offset:17472
	ds_read_b128 v[192:195], v173 offset:17504
	s_waitcnt lgkmcnt(6)
	v_mfma_scale_f32_32x32x64_f8f6f4 v[2:17], v[180:183], v[196:203], v[2:17], v159, v159 op_sel_hi:[0,0,0] cbsz:4
	ds_read_b128 v[180:183], v157 offset:64
	ds_read_b128 v[196:199], v173 offset:17536
	ds_read_b128 v[200:203], v173 offset:17568
	s_waitcnt lgkmcnt(6)
; #define LAS __attribute__((address_space(3)))
; __device__ __forceinline__ void phase_gather_u_mfma(LAS unsigned char* lds, const bf16* X, const int* EID, float* GATE, const unsigned char* U4, const float* DQU, const float* DQV) {
;     ...
;         for (int q = 0; q < 4; ++q) {
; #pragma unroll
;             for (int j = 0; j < 16; ++j) *(LAS v4u*)(rows + hh * 528 + 16 * n + j * 1056) = ring[j];
;             __builtin_amdgcn_sched_barrier(0);
;             { const int qn = q + 1;
;     ...
;             for (int ks = 0; ks < 8; ++ks) {
;                 const v4u a4 = *(const LAS v4u*)(rows + n * 528 + 16 * hh + 32 * ks);
;                 v8i A, B;
;                 A[0] = (int)a4.x; A[1] = (int)a4.y; A[2] = (int)a4.z; A[3] = (int)a4.w; A[4] = 0; A[5] = 0; A[6] = 0; A[7] = 0;
;                 B[0] = (int)xf0[ks].x; B[1] = (int)xf0[ks].y; B[2] = (int)xf0[ks].z; B[3] = (int)xf0[ks].w; B[4] = (int)xf1[ks].x; B[5] = (int)xf1[ks].y; B[6] = (int)xf1[ks].z; B[7] = (int)xf1[ks].w;
;                 acc = __builtin_amdgcn_mfma_scale_f32_32x32x64_f8f6f4(A, B, acc, 4, 0, 0, 0x7f7f7f7f, 0, 0x7f7f7f7f);
;                 if ((ks & 1) == 1) __builtin_amdgcn_sched_barrier(0);
;             }
;             unsigned xo = 16u * (unsigned)hh; asm volatile("" : "+v"(xo));
; #pragma unroll 2
;             for (int ks = 8; ks < 16; ++ks) {
;                 const v4u a4 = *(const LAS v4u*)(rows + n * 528 + 16 * hh + 32 * ks);
;                 const v4u b0 = *(const LAS v4u*)(x8 + xo + 64 * ks), b1 = *(const LAS v4u*)(x8 + xo + 64 * ks + 32);
;                 v8i A, B;
;                 A[0] = (int)a4.x; A[1] = (int)a4.y; A[2] = (int)a4.z; A[3] = (int)a4.w; A[4] = 0; A[5] = 0; A[6] = 0; A[7] = 0;
;                 B[0] = (int)b0.x; B[1] = (int)b0.y; B[2] = (int)b0.z; B[3] = (int)b0.w; B[4] = (int)b1.x; B[5] = (int)b1.y; B[6] = (int)b1.z; B[7] = (int)b1.w;
;                 acc = __builtin_amdgcn_mfma_scale_f32_32x32x64_f8f6f4(A, B, acc, 4, 0, 0, 0x7f7f7f7f, 0, 0x7f7f7f7f);
;             }
;             if (n == 0) {
; #pragma unroll
;                 for (int r = 0; r < 16; ++r) { const float av = acc[r]; *(LAS float*)(x8 + 1024 + 4 * ((r & 3) + 8 * (r >> 2) + 4 * hh)) = av; }
;             }
;             const float act = *(const LAS float*)(x8 + 1024 + 4 * n);
;             if (hh == (q & 1)) { if (q >> 1) act1 = act; else act0 = act; }
	v_mfma_scale_f32_32x32x64_f8f6f4 v[2:17], v[236:239], v[240:247], v[2:17], v159, v159 op_sel_hi:[0,0,0] cbsz:4
	ds_read_b128 v[236:239], v157 offset:96
	ds_read_b128 v[240:243], v173 offset:17600
	ds_read_b128 v[244:247], v173 offset:17632
	s_waitcnt lgkmcnt(6)
	v_mfma_scale_f32_32x32x64_f8f6f4 v[2:17], v[176:179], v[188:195], v[2:17], v159, v159 op_sel_hi:[0,0,0] cbsz:4
	ds_read_b128 v[176:179], v157 offset:128
	ds_read_b128 v[188:191], v173 offset:17664
	ds_read_b128 v[192:195], v173 offset:17696
	s_waitcnt lgkmcnt(6)
	v_mfma_scale_f32_32x32x64_f8f6f4 v[2:17], v[180:183], v[196:203], v[2:17], v159, v159 op_sel_hi:[0,0,0] cbsz:4
	ds_read_b128 v[180:183], v157 offset:160
	ds_read_b128 v[196:199], v173 offset:17728
	ds_read_b128 v[200:203], v173 offset:17760
	s_waitcnt lgkmcnt(6)
	v_mfma_scale_f32_32x32x64_f8f6f4 v[2:17], v[236:239], v[240:247], v[2:17], v159, v159 op_sel_hi:[0,0,0] cbsz:4
	ds_read_b128 v[236:239], v157 offset:192
	ds_read_b128 v[240:243], v173 offset:17792
	ds_read_b128 v[244:247], v173 offset:17824
	s_waitcnt lgkmcnt(6)
	v_mfma_scale_f32_32x32x64_f8f6f4 v[2:17], v[176:179], v[188:195], v[2:17], v159, v159 op_sel_hi:[0,0,0] cbsz:4
	ds_read_b128 v[176:179], v157 offset:224
	ds_read_b128 v[188:191], v173 offset:17856
	ds_read_b128 v[192:195], v173 offset:17888
	s_waitcnt lgkmcnt(6)
	v_mfma_scale_f32_32x32x64_f8f6f4 v[2:17], v[180:183], v[196:203], v[2:17], v159, v159 op_sel_hi:[0,0,0] cbsz:4
	s_waitcnt lgkmcnt(3)
	v_mfma_scale_f32_32x32x64_f8f6f4 v[2:17], v[236:239], v[240:247], v[2:17], v159, v159 op_sel_hi:[0,0,0] cbsz:4
	s_waitcnt lgkmcnt(0)
	v_mfma_scale_f32_32x32x64_f8f6f4 v[2:17], v[176:179], v[188:195], v[2:17], v159, v159 op_sel_hi:[0,0,0] cbsz:4
	s_and_saveexec_b64 s[2:3], s[6:7]
	s_cbranch_execz .Lud8_g2
	s_nop 15
	s_nop 0
	ds_write_b128 v173, v[2:5] offset:17920
	ds_write_b128 v173, v[6:9] offset:17952
	ds_write_b128 v173, v[10:13] offset:17984
	ds_write_b128 v173, v[14:17] offset:18016
.Lud8_g2:
	s_or_b64 exec, exec, s[2:3]
	s_nop 15
	ds_read_b32 v154, v163 offset:17920
	v_readlane_b32 s2, v166, 32
	v_readlane_b32 s3, v166, 33
	s_waitcnt vmcnt(37)
	ds_write_b128 v161, v[18:21]
	v_mov_b32_e32 v248, s3
	v_mov_b32_e32 v235, s2
	v_cndmask_b32_e64 v248, v248, v235, s[4:5]
	v_lshl_or_b32 v248, v248, 9, v1
	global_load_dwordx4 v[18:21], v248, s[0:1]
	v_readlane_b32 s2, v166, 34
	v_readlane_b32 s3, v166, 35
	s_waitcnt vmcnt(37)
	ds_write_b128 v161, v[22:25] offset:1056
	v_mov_b32_e32 v249, s3
	v_mov_b32_e32 v235, s2
	v_cndmask_b32_e64 v249, v249, v235, s[4:5]
	v_lshl_or_b32 v249, v249, 9, v1
	global_load_dwordx4 v[22:25], v249, s[0:1]
	v_readlane_b32 s2, v166, 36
	v_readlane_b32 s3, v166, 37
	s_waitcnt vmcnt(37)
	ds_write_b128 v161, v[26:29] offset:2112
	v_mov_b32_e32 v250, s3
	v_mov_b32_e32 v235, s2
	v_cndmask_b32_e64 v250, v250, v235, s[4:5]
	v_lshl_or_b32 v250, v250, 9, v1
	global_load_dwordx4 v[26:29], v250, s[0:1]
	v_readlane_b32 s2, v166, 38
	v_readlane_b32 s3, v166, 39
	s_waitcnt vmcnt(37)
	ds_write_b128 v161, v[30:33] offset:3168
	v_mov_b32_e32 v251, s3
	v_mov_b32_e32 v235, s2
	v_cndmask_b32_e64 v251, v251, v235, s[4:5]
	v_lshl_or_b32 v251, v251, 9, v1
	global_load_dwordx4 v[30:33], v251, s[0:1]
	v_readlane_b32 s2, v166, 40
	v_readlane_b32 s3, v166, 41
	s_waitcnt vmcnt(37)
	ds_write_b128 v161, v[34:37] offset:4224
	v_mov_b32_e32 v252, s3
	v_mov_b32_e32 v235, s2
	v_cndmask_b32_e64 v252, v252, v235, s[4:5]
	v_lshl_or_b32 v252, v252, 9, v1
	global_load_dwordx4 v[34:37], v252, s[0:1]
	v_readlane_b32 s2, v166, 42
	v_readlane_b32 s3, v166, 43
	s_waitcnt vmcnt(37)
	ds_write_b128 v161, v[38:41] offset:5280
	v_mov_b32_e32 v253, s3
	v_mov_b32_e32 v235, s2
	v_cndmask_b32_e64 v253, v253, v235, s[4:5]
	v_lshl_or_b32 v253, v253, 9, v1
	global_load_dwordx4 v[38:41], v253, s[0:1]
	v_readlane_b32 s2, v166, 44
	v_readlane_b32 s3, v166, 45
	s_waitcnt vmcnt(37)
	ds_write_b128 v161, v[42:45] offset:6336
	v_mov_b32_e32 v254, s3
	v_mov_b32_e32 v235, s2
	v_cndmask_b32_e64 v254, v254, v235, s[4:5]
	v_lshl_or_b32 v254, v254, 9, v1
	global_load_dwordx4 v[42:45], v254, s[0:1]
	v_readlane_b32 s2, v166, 46
	v_readlane_b32 s3, v166, 47
	s_waitcnt vmcnt(37)
	ds_write_b128 v161, v[46:49] offset:7392
	v_mov_b32_e32 v204, s3
	v_mov_b32_e32 v235, s2
	v_cndmask_b32_e64 v204, v204, v235, s[4:5]
	v_lshl_or_b32 v204, v204, 9, v1
	global_load_dwordx4 v[46:49], v204, s[0:1]
	v_readlane_b32 s2, v166, 48
	v_readlane_b32 s3, v166, 49
	s_waitcnt vmcnt(37)
	ds_write_b128 v161, v[50:53] offset:8448
	v_mov_b32_e32 v205, s3
	v_mov_b32_e32 v235, s2
	v_cndmask_b32_e64 v205, v205, v235, s[4:5]
	v_lshl_or_b32 v205, v205, 9, v1
	global_load_dwordx4 v[50:53], v205, s[0:1]
	v_readlane_b32 s2, v166, 50
	v_readlane_b32 s3, v166, 51
	s_waitcnt vmcnt(37)
	ds_write_b128 v161, v[54:57] offset:9504
	v_mov_b32_e32 v206, s3
	v_mov_b32_e32 v235, s2
	v_cndmask_b32_e64 v206, v206, v235, s[4:5]
	v_lshl_or_b32 v206, v206, 9, v1
	global_load_dwordx4 v[54:57], v206, s[0:1]
	v_readlane_b32 s2, v166, 52
	v_readlane_b32 s3, v166, 53
	s_waitcnt vmcnt(37)
	ds_write_b128 v161, v[58:61] offset:10560
	v_mov_b32_e32 v207, s3
	v_mov_b32_e32 v235, s2
	v_cndmask_b32_e64 v207, v207, v235, s[4:5]
	v_lshl_or_b32 v207, v207, 9, v1
	global_load_dwordx4 v[58:61], v207, s[0:1]
	v_readlane_b32 s2, v166, 54
	v_readlane_b32 s3, v166, 55
	s_waitcnt vmcnt(37)
	ds_write_b128 v161, v[62:65] offset:11616
	v_mov_b32_e32 v230, s3
	v_mov_b32_e32 v235, s2
	v_cndmask_b32_e64 v230, v230, v235, s[4:5]
	v_lshl_or_b32 v230, v230, 9, v1
	global_load_dwordx4 v[62:65], v230, s[0:1]
	v_readlane_b32 s2, v166, 56
	v_readlane_b32 s3, v166, 57
	s_waitcnt vmcnt(37)
; __device__ __forceinline__ void phase_gather_u_mfma(LAS unsigned char* lds, const bf16* X, const int* EID, float* GATE, const unsigned char* U4, const float* DQU, const float* DQV) {
;     ...
;         for (int q = 0; q < 4; ++q) {
; #pragma unroll
;             for (int j = 0; j < 16; ++j) *(LAS v4u*)(rows + hh * 528 + 16 * n + j * 1056) = ring[j];
;             __builtin_amdgcn_sched_barrier(0);
;             { const int qn = q + 1;
;               const int er = (qn >= 4) ? ne0 : ((qn >> 1) ? e1 : e0); const int lb = (qn >= 4) ? 0 : 32 * (qn & 1);
; #pragma unroll
;               for (int j = 0; j < 16; ++j) ULOADA(j, er, lb, j) }
;             __builtin_amdgcn_sched_barrier(0);
;             f32x16 acc;
; #pragma unroll
;             for (int r = 0; r < 16; ++r) acc[r] = 0.f;
; #pragma unroll
;             for (int ks = 0; ks < 8; ++ks) {
;                 const v4u a4 = *(const LAS v4u*)(rows + n * 528 + 16 * hh + 32 * ks);
;                 v8i A, B;
;                 A[0] = (int)a4.x; A[1] = (int)a4.y; A[2] = (int)a4.z; A[3] = (int)a4.w; A[4] = 0; A[5] = 0; A[6] = 0; A[7] = 0;
;                 B[0] = (int)xf0[ks].x; B[1] = (int)xf0[ks].y; B[2] = (int)xf0[ks].z; B[3] = (int)xf0[ks].w; B[4] = (int)xf1[ks].x; B[5] = (int)xf1[ks].y; B[6] = (int)xf1[ks].z; B[7] = (int)xf1[ks].w;
;                 acc = __builtin_amdgcn_mfma_scale_f32_32x32x64_f8f6f4(A, B, acc, 4, 0, 0, 0x7f7f7f7f, 0, 0x7f7f7f7f);
;                 if ((ks & 1) == 1) __builtin_amdgcn_sched_barrier(0);
;             }
;             unsigned xo = 16u * (unsigned)hh; asm volatile("" : "+v"(xo));
; #pragma unroll 2
;             for (int ks = 8; ks < 16; ++ks) {
;                 const v4u a4 = *(const LAS v4u*)(rows + n * 528 + 16 * hh + 32 * ks);
;                 const v4u b0 = *(const LAS v4u*)(x8 + xo + 64 * ks), b1 = *(const LAS v4u*)(x8 + xo + 64 * ks + 32);
;                 v8i A, B;
;                 A[0] = (int)a4.x; A[1] = (int)a4.y; A[2] = (int)a4.z; A[3] = (int)a4.w; A[4] = 0; A[5] = 0; A[6] = 0; A[7] = 0;
;                 B[0] = (int)b0.x; B[1] = (int)b0.y; B[2] = (int)b0.z; B[3] = (int)b0.w; B[4] = (int)b1.x; B[5] = (int)b1.y; B[6] = (int)b1.z; B[7] = (int)b1.w;
;                 acc = __builtin_amdgcn_mfma_scale_f32_32x32x64_f8f6f4(A, B, acc, 4, 0, 0, 0x7f7f7f7f, 0, 0x7f7f7f7f);
;             }
;             if (n == 0) {
; #pragma unroll
	ds_write_b128 v161, v[66:69] offset:12672
	v_mov_b32_e32 v231, s3
	v_mov_b32_e32 v235, s2
	v_cndmask_b32_e64 v231, v231, v235, s[4:5]
	v_lshl_or_b32 v231, v231, 9, v1
	global_load_dwordx4 v[66:69], v231, s[0:1]
	v_readlane_b32 s2, v166, 58
	v_readlane_b32 s3, v166, 59
	s_waitcnt vmcnt(37)
	ds_write_b128 v161, v[70:73] offset:13728
	v_mov_b32_e32 v232, s3
	v_mov_b32_e32 v235, s2
	v_cndmask_b32_e64 v232, v232, v235, s[4:5]
	v_lshl_or_b32 v232, v232, 9, v1
	global_load_dwordx4 v[70:73], v232, s[0:1]
	v_readlane_b32 s2, v166, 60
	v_readlane_b32 s3, v166, 61
	s_waitcnt vmcnt(37)
	ds_write_b128 v161, v[74:77] offset:14784
	v_mov_b32_e32 v233, s3
	v_mov_b32_e32 v235, s2
	v_cndmask_b32_e64 v233, v233, v235, s[4:5]
	v_lshl_or_b32 v233, v233, 9, v1
	global_load_dwordx4 v[74:77], v233, s[0:1]
	v_readlane_b32 s2, v166, 62
	v_readlane_b32 s3, v166, 63
	s_waitcnt vmcnt(37)
	ds_write_b128 v161, v[78:81] offset:15840
	v_mov_b32_e32 v234, s3
	v_mov_b32_e32 v235, s2
	v_cndmask_b32_e64 v234, v234, v235, s[4:5]
	v_lshl_or_b32 v234, v234, 9, v1
	global_load_dwordx4 v[78:81], v234, s[0:1]
	ds_read_b128 v[176:179], v162
	ds_read_b128 v[188:191], v173 offset:16896
	ds_read_b128 v[192:195], v173 offset:16928
	ds_read_b128 v[180:183], v162 offset:32
	ds_read_b128 v[196:199], v173 offset:16960
	ds_read_b128 v[200:203], v173 offset:16992
	ds_read_b128 v[236:239], v162 offset:64
	ds_read_b128 v[240:243], v173 offset:17024
	ds_read_b128 v[244:247], v173 offset:17056
	s_waitcnt lgkmcnt(6)
	v_mfma_scale_f32_32x32x64_f8f6f4 v[2:17], v[176:179], v[188:195], 0, v159, v159 op_sel_hi:[0,0,0] cbsz:4
	ds_read_b128 v[176:179], v162 offset:96
	ds_read_b128 v[188:191], v173 offset:17088
	ds_read_b128 v[192:195], v173 offset:17120
	s_waitcnt lgkmcnt(6)
	v_mfma_scale_f32_32x32x64_f8f6f4 v[2:17], v[180:183], v[196:203], v[2:17], v159, v159 op_sel_hi:[0,0,0] cbsz:4
	ds_read_b128 v[180:183], v162 offset:128
	ds_read_b128 v[196:199], v173 offset:17152
	ds_read_b128 v[200:203], v173 offset:17184
	s_waitcnt lgkmcnt(6)
	v_mfma_scale_f32_32x32x64_f8f6f4 v[2:17], v[236:239], v[240:247], v[2:17], v159, v159 op_sel_hi:[0,0,0] cbsz:4
	ds_read_b128 v[236:239], v162 offset:160
	ds_read_b128 v[240:243], v173 offset:17216
	ds_read_b128 v[244:247], v173 offset:17248
	s_waitcnt lgkmcnt(6)
	v_mfma_scale_f32_32x32x64_f8f6f4 v[2:17], v[176:179], v[188:195], v[2:17], v159, v159 op_sel_hi:[0,0,0] cbsz:4
	ds_read_b128 v[176:179], v162 offset:192
	ds_read_b128 v[188:191], v173 offset:17280
	ds_read_b128 v[192:195], v173 offset:17312
	s_waitcnt lgkmcnt(6)
	v_mfma_scale_f32_32x32x64_f8f6f4 v[2:17], v[180:183], v[196:203], v[2:17], v159, v159 op_sel_hi:[0,0,0] cbsz:4
	ds_read_b128 v[180:183], v162 offset:224
	ds_read_b128 v[196:199], v173 offset:17344
	ds_read_b128 v[200:203], v173 offset:17376
	s_waitcnt lgkmcnt(6)
	v_mfma_scale_f32_32x32x64_f8f6f4 v[2:17], v[236:239], v[240:247], v[2:17], v159, v159 op_sel_hi:[0,0,0] cbsz:4
	ds_read_b128 v[236:239], v157
	ds_read_b128 v[240:243], v173 offset:17408
	ds_read_b128 v[244:247], v173 offset:17440
	s_waitcnt lgkmcnt(6)
	v_mfma_scale_f32_32x32x64_f8f6f4 v[2:17], v[176:179], v[188:195], v[2:17], v159, v159 op_sel_hi:[0,0,0] cbsz:4
	ds_read_b128 v[176:179], v157 offset:32
	ds_read_b128 v[188:191], v173 offset:17472
	ds_read_b128 v[192:195], v173 offset:17504
	s_waitcnt lgkmcnt(6)
	v_mfma_scale_f32_32x32x64_f8f6f4 v[2:17], v[180:183], v[196:203], v[2:17], v159, v159 op_sel_hi:[0,0,0] cbsz:4
	ds_read_b128 v[180:183], v157 offset:64
	ds_read_b128 v[196:199], v173 offset:17536
	ds_read_b128 v[200:203], v173 offset:17568
	s_waitcnt lgkmcnt(6)
	v_mfma_scale_f32_32x32x64_f8f6f4 v[2:17], v[236:239], v[240:247], v[2:17], v159, v159 op_sel_hi:[0,0,0] cbsz:4
	ds_read_b128 v[236:239], v157 offset:96
	ds_read_b128 v[240:243], v173 offset:17600
	ds_read_b128 v[244:247], v173 offset:17632
	s_waitcnt lgkmcnt(6)
	v_mfma_scale_f32_32x32x64_f8f6f4 v[2:17], v[176:179], v[188:195], v[2:17], v159, v159 op_sel_hi:[0,0,0] cbsz:4
	ds_read_b128 v[176:179], v157 offset:128
	ds_read_b128 v[188:191], v173 offset:17664
	ds_read_b128 v[192:195], v173 offset:17696
	s_waitcnt lgkmcnt(6)
	v_mfma_scale_f32_32x32x64_f8f6f4 v[2:17], v[180:183], v[196:203], v[2:17], v159, v159 op_sel_hi:[0,0,0] cbsz:4
	ds_read_b128 v[180:183], v157 offset:160
	ds_read_b128 v[196:199], v173 offset:17728
	ds_read_b128 v[200:203], v173 offset:17760
	s_waitcnt lgkmcnt(6)
	v_mfma_scale_f32_32x32x64_f8f6f4 v[2:17], v[236:239], v[240:247], v[2:17], v159, v159 op_sel_hi:[0,0,0] cbsz:4
	ds_read_b128 v[236:239], v157 offset:192
	ds_read_b128 v[240:243], v173 offset:17792
	ds_read_b128 v[244:247], v173 offset:17824
	s_waitcnt lgkmcnt(6)
	v_mfma_scale_f32_32x32x64_f8f6f4 v[2:17], v[176:179], v[188:195], v[2:17], v159, v159 op_sel_hi:[0,0,0] cbsz:4
	ds_read_b128 v[176:179], v157 offset:224
	ds_read_b128 v[188:191], v173 offset:17856
	ds_read_b128 v[192:195], v173 offset:17888
	s_waitcnt lgkmcnt(6)
	v_mfma_scale_f32_32x32x64_f8f6f4 v[2:17], v[180:183], v[196:203], v[2:17], v159, v159 op_sel_hi:[0,0,0] cbsz:4
	s_waitcnt lgkmcnt(3)
	v_mfma_scale_f32_32x32x64_f8f6f4 v[2:17], v[236:239], v[240:247], v[2:17], v159, v159 op_sel_hi:[0,0,0] cbsz:4
	s_waitcnt lgkmcnt(0)
	v_mfma_scale_f32_32x32x64_f8f6f4 v[2:17], v[176:179], v[188:195], v[2:17], v159, v159 op_sel_hi:[0,0,0] cbsz:4
	s_and_saveexec_b64 s[2:3], s[6:7]
	s_cbranch_execz .Lud8_g3
	s_nop 15
	s_nop 0
	ds_write_b128 v173, v[2:5] offset:17920
	ds_write_b128 v173, v[6:9] offset:17952
	ds_write_b128 v173, v[10:13] offset:17984
	ds_write_b128 v173, v[14:17] offset:18016

; #define GAS __attribute__((address_space(1)))
; #define ULOADA(slot, ereg, lb, j_) { const int ea_ = __builtin_amdgcn_readlane((ereg), (lb) + 2 * (j_)), eb_ = __builtin_amdgcn_readlane((ereg), (lb) + 2 * (j_) + 1); const int el_ = hh ? eb_ : ea_; \
;         ring[slot] = *(const GAS v4u*)(U4 + (((unsigned)el_ << 9) + laneoff)); }
; __device__ __forceinline__ void phase_gather_u_mfma(LAS unsigned char* lds, const bf16* X, const int* EID, float* GATE, const unsigned char* U4, const float* DQU, const float* DQV) {
;     ...
;     int t = gw;
;     if (t < T) {
;     int e0 = EID[(size_t)t * 128 + lane], e1 = EID[(size_t)t * 128 + 64 + lane];
;     v4u ring[16];
;     ...
; #pragma unroll
;     for (int j = 0; j < 16; ++j) ULOADA(j, e0, 0, j)
;     for (;;) {
;         const int tn = t + NGW; const bool has_next = tn < T;
;         int ne0 = e0, ne1 = e1;
;         if (has_next) { ne0 = EID[(size_t)tn * 128 + lane]; ne1 = EID[(size_t)tn * 128 + 64 + lane]; }
;         const float gt0 = GATE[(size_t)t * 128 + lane], gt1 = GATE[(size_t)t * 128 + 64 + lane];
;         const float dqu0 = DQU[e0], dqu1 = DQU[e1], dqv0 = DQV[e0], dqv1 = DQV[e1];
;         { const v4u xa = *((const GAS v4u*)(X + (size_t)t * D) + 2 * lane), xb = *((const GAS v4u*)(X + (size_t)t * D) + 2 * lane + 1);
.LBB0_1893:
	s_cmp_lt_i32 s68, 17
	s_cselect_b64 s[8:9], -1, 0
	s_and_b64 s[0:1], s[8:9], s[6:7]
	s_andn2_b64 vcc, exec, s[0:1]
	s_cbranch_vccnz .LBB0_1923
	v_readfirstlane_b32 s1, v0
	s_lshl_b32 s0, s88, 3
	s_lshr_b32 s2, s1, 6
	s_add_i32 s18, s2, s0
	s_cmpk_gt_i32 s18, 0x7fff
	s_cbranch_scc1 .LBB0_1923
	s_add_u32 s0, s82, 0x2800000
	s_addc_u32 s1, s83, 0
	s_add_u32 s10, s82, 0x1d20000
	s_addc_u32 s11, s83, 0
	s_add_u32 s12, s82, 0x1d30000
	s_waitcnt vmcnt(0)
	v_and_b32_e32 v3, 63, v0
	s_addc_u32 s13, s83, 0
	v_lshlrev_b32_e32 v4, 2, v3
	v_mov_b32_e32 v5, 0
	s_ashr_i32 s19, s18, 31
	v_lshl_add_u64 v[146:147], s[60:61], 0, v[4:5]
	s_lshl_b64 s[4:5], s[18:19], 9
	v_lshl_add_u64 v[6:7], v[146:147], 0, s[4:5]
	global_load_dword v2, v[6:7], off nt
	global_load_dword v154, v[6:7], off offset:256 nt
	v_and_b32_e32 v8, 31, v0
	v_lshlrev_b32_e32 v1, 4, v8
	s_mulk_i32 s2, 0x4680
	v_lshl_add_u64 v[148:149], s[70:71], 0, v[4:5]
	v_lshlrev_b32_e32 v156, 4, v186
	v_mov_b32_e32 v159, 0x7f7f7f7f
	v_mov_b32_e32 v160, 0x3ba10414
	s_brev_b32 s33, -2
	v_mov_b32_e32 v164, 0xb9c68948
	v_mov_b32_e32 v165, 0x7f800000
	s_waitcnt vmcnt(0)
	v_cmp_gt_u32_e64 s[4:5], 32, v3
	s_add_i32 s21, s2, 0
	s_movk_i32 s3, 0x210
	v_mov_b32_e32 v4, s21
	v_lshlrev_b32_e32 v7, 4, v3
	v_mad_u32_u24 v9, v186, s3, v4
	v_mad_u32_u24 v10, v8, s3, v4
	v_lshlrev_b32_e32 v4, 5, v3
	v_mov_b32_e32 v3, s2
	v_readlane_b32 s6, v255, 9
	v_mad_u32_u24 v3, v8, s3, v3
	v_readlane_b32 s7, v255, 10
	v_lshlrev_b32_e32 v6, 2, v8
	v_add3_u32 v3, v3, v156, 0
	s_lshl_b32 s20, s6, 3
	v_cmp_eq_u32_e64 s[6:7], 0, v8
	v_lshl_add_u64 v[150:151], s[62:63], 0, v[4:5]
	v_add_u32_e32 v157, 0x100, v3
	s_add_i32 s22, s21, 0x4400
	v_add_u32_e32 v158, s21, v7
	s_mov_b32 s23, 0x378e98ab
	s_mov_b32 s24, 0x3b7cd369
	s_mov_b32 s25, 0xbcc618b2
	s_mov_b32 s26, 0x3dda74e4
	s_mov_b32 s27, 0x3f228afd
	s_mov_b32 s28, 0x3e03c728
	s_mov_b32 s29, 0xbfb8aa3b
	s_mov_b32 s30, 0x42ce8ed0
	s_mov_b32 s31, 0xc2b17218
	v_add_u32_e32 v161, v9, v1
	v_add_u32_e32 v162, v10, v156
	v_add_u32_e32 v163, s21, v6
	v_lshlrev_b32_e32 v226, 2, v186
	v_add_u32_e32 v227, 0x80, v226
	s_ashr_i32 s3, s18, 31
	s_mov_b32 s2, s18
	s_lshl_b64 s[2:3], s[2:3], 11
	v_lshl_add_u64 v[228:229], v[150:151], 0, s[2:3]
	global_load_dwordx4 v[212:215], v[228:229], off nt
	global_load_dwordx4 v[216:219], v[228:229], off offset:16 nt
	s_ashr_i32 s3, s18, 31
	s_mov_b32 s2, s18
	s_lshl_b64 s[2:3], s[2:3], 9
	v_lshl_add_u64 v[228:229], v[148:149], 0, s[2:3]
	global_load_dword v220, v[228:229], off nt
	global_load_dword v221, v[228:229], off offset:256 nt
	v_mov_b32_e32 v228, v2
	v_ashrrev_i32_e32 v229, 31, v2
	v_lshlrev_b64 v[228:229], 3, v[228:229]
	v_lshl_add_u64 v[228:229], s[10:11], 0, v[228:229]
	global_load_dwordx2 v[222:223], v[228:229], off
	v_mov_b32_e32 v228, v154
	v_ashrrev_i32_e32 v229, 31, v154
	v_lshlrev_b64 v[228:229], 3, v[228:229]
	v_lshl_add_u64 v[228:229], s[10:11], 0, v[228:229]
	global_load_dwordx2 v[224:225], v[228:229], off
	ds_bpermute_b32 v82, v226, v2
	ds_bpermute_b32 v86, v226, v2 offset:8
	ds_bpermute_b32 v90, v226, v2 offset:16
	ds_bpermute_b32 v94, v226, v2 offset:24
	ds_bpermute_b32 v98, v226, v2 offset:32
	ds_bpermute_b32 v102, v226, v2 offset:40
	ds_bpermute_b32 v106, v226, v2 offset:48
	ds_bpermute_b32 v110, v226, v2 offset:56
	ds_bpermute_b32 v114, v226, v2 offset:64
	ds_bpermute_b32 v118, v226, v2 offset:72
	ds_bpermute_b32 v122, v226, v2 offset:80
	ds_bpermute_b32 v126, v226, v2 offset:88
	ds_bpermute_b32 v130, v226, v2 offset:96
	ds_bpermute_b32 v134, v226, v2 offset:104
	ds_bpermute_b32 v138, v226, v2 offset:112
	ds_bpermute_b32 v142, v226, v2 offset:120
	s_waitcnt lgkmcnt(15)
	v_lshl_or_b32 v82, v82, 9, v1
	global_load_dwordx4 v[82:85], v82, s[0:1]
	s_waitcnt lgkmcnt(14)
; #define ULOADA(slot, ereg, lb, j_) { const int ea_ = __builtin_amdgcn_readlane((ereg), (lb) + 2 * (j_)), eb_ = __builtin_amdgcn_readlane((ereg), (lb) + 2 * (j_) + 1); const int el_ = hh ? eb_ : ea_; \
;         ring[slot] = *(const GAS v4u*)(U4 + (((unsigned)el_ << 9) + laneoff)); }
; __device__ __forceinline__ void phase_gather_u_mfma(LAS unsigned char* lds, const bf16* X, const int* EID, float* GATE, const unsigned char* U4, const float* DQU, const float* DQV) {
;     ...
; #pragma unroll
;     for (int j = 0; j < 16; ++j) ULOADA(j, e0, 0, j)
	v_lshl_or_b32 v86, v86, 9, v1
	global_load_dwordx4 v[86:89], v86, s[0:1]
	s_waitcnt lgkmcnt(13)
	v_lshl_or_b32 v90, v90, 9, v1
	global_load_dwordx4 v[90:93], v90, s[0:1]
	s_waitcnt lgkmcnt(12)
	v_lshl_or_b32 v94, v94, 9, v1
	global_load_dwordx4 v[94:97], v94, s[0:1]
	s_waitcnt lgkmcnt(11)
	v_lshl_or_b32 v98, v98, 9, v1
	global_load_dwordx4 v[98:101], v98, s[0:1]
	s_waitcnt lgkmcnt(10)
	v_lshl_or_b32 v102, v102, 9, v1
	global_load_dwordx4 v[102:105], v102, s[0:1]
	s_waitcnt lgkmcnt(9)
	v_lshl_or_b32 v106, v106, 9, v1
	global_load_dwordx4 v[106:109], v106, s[0:1]
	s_waitcnt lgkmcnt(8)
	v_lshl_or_b32 v110, v110, 9, v1
	global_load_dwordx4 v[110:113], v110, s[0:1]
	s_waitcnt lgkmcnt(7)
	v_lshl_or_b32 v114, v114, 9, v1
	global_load_dwordx4 v[114:117], v114, s[0:1]
	s_waitcnt lgkmcnt(6)
	v_lshl_or_b32 v118, v118, 9, v1
	global_load_dwordx4 v[118:121], v118, s[0:1]
	s_waitcnt lgkmcnt(5)
	v_lshl_or_b32 v122, v122, 9, v1
	global_load_dwordx4 v[122:125], v122, s[0:1]
	s_waitcnt lgkmcnt(4)
	v_lshl_or_b32 v126, v126, 9, v1
	global_load_dwordx4 v[126:129], v126, s[0:1]
	s_waitcnt lgkmcnt(3)
	v_lshl_or_b32 v130, v130, 9, v1
	global_load_dwordx4 v[130:133], v130, s[0:1]
	s_waitcnt lgkmcnt(2)
	v_lshl_or_b32 v134, v134, 9, v1
	global_load_dwordx4 v[134:137], v134, s[0:1]
	s_waitcnt lgkmcnt(1)
	v_lshl_or_b32 v138, v138, 9, v1
	global_load_dwordx4 v[138:141], v138, s[0:1]
	s_waitcnt lgkmcnt(0)
	v_lshl_or_b32 v142, v142, 9, v1
	global_load_dwordx4 v[142:145], v142, s[0:1]
	ds_bpermute_b32 v18, v227, v2
	ds_bpermute_b32 v22, v227, v2 offset:8
	ds_bpermute_b32 v26, v227, v2 offset:16
	ds_bpermute_b32 v30, v227, v2 offset:24
	ds_bpermute_b32 v34, v227, v2 offset:32
	ds_bpermute_b32 v38, v227, v2 offset:40
	ds_bpermute_b32 v42, v227, v2 offset:48
	ds_bpermute_b32 v46, v227, v2 offset:56
	ds_bpermute_b32 v50, v227, v2 offset:64
	ds_bpermute_b32 v54, v227, v2 offset:72
	ds_bpermute_b32 v58, v227, v2 offset:80
	ds_bpermute_b32 v62, v227, v2 offset:88
	ds_bpermute_b32 v66, v227, v2 offset:96
	ds_bpermute_b32 v70, v227, v2 offset:104
	ds_bpermute_b32 v74, v227, v2 offset:112
	ds_bpermute_b32 v78, v227, v2 offset:120
	s_waitcnt lgkmcnt(15)
	v_lshl_or_b32 v18, v18, 9, v1
	global_load_dwordx4 v[18:21], v18, s[0:1]
	s_waitcnt lgkmcnt(14)
	v_lshl_or_b32 v22, v22, 9, v1
	global_load_dwordx4 v[22:25], v22, s[0:1]
	s_waitcnt lgkmcnt(13)
	v_lshl_or_b32 v26, v26, 9, v1
	global_load_dwordx4 v[26:29], v26, s[0:1]
	s_waitcnt lgkmcnt(12)
	v_lshl_or_b32 v30, v30, 9, v1
	global_load_dwordx4 v[30:33], v30, s[0:1]
	s_waitcnt lgkmcnt(11)
	v_lshl_or_b32 v34, v34, 9, v1
	global_load_dwordx4 v[34:37], v34, s[0:1]
	s_waitcnt lgkmcnt(10)
	v_lshl_or_b32 v38, v38, 9, v1
	global_load_dwordx4 v[38:41], v38, s[0:1]
	s_waitcnt lgkmcnt(9)
	v_lshl_or_b32 v42, v42, 9, v1
	global_load_dwordx4 v[42:45], v42, s[0:1]
	s_waitcnt lgkmcnt(8)
	v_lshl_or_b32 v46, v46, 9, v1
	global_load_dwordx4 v[46:49], v46, s[0:1]
	s_waitcnt lgkmcnt(7)
	v_lshl_or_b32 v50, v50, 9, v1
	global_load_dwordx4 v[50:53], v50, s[0:1]
	s_waitcnt lgkmcnt(6)
	v_lshl_or_b32 v54, v54, 9, v1
	global_load_dwordx4 v[54:57], v54, s[0:1]
	s_waitcnt lgkmcnt(5)
	v_lshl_or_b32 v58, v58, 9, v1
	global_load_dwordx4 v[58:61], v58, s[0:1]
	s_waitcnt lgkmcnt(4)
	v_lshl_or_b32 v62, v62, 9, v1
	global_load_dwordx4 v[62:65], v62, s[0:1]
	s_waitcnt lgkmcnt(3)
	v_lshl_or_b32 v66, v66, 9, v1
	global_load_dwordx4 v[66:69], v66, s[0:1]
	s_waitcnt lgkmcnt(2)
	v_lshl_or_b32 v70, v70, 9, v1
	global_load_dwordx4 v[70:73], v70, s[0:1]
	s_waitcnt lgkmcnt(1)
	v_lshl_or_b32 v74, v74, 9, v1
	global_load_dwordx4 v[74:77], v74, s[0:1]
	s_waitcnt lgkmcnt(0)
	v_lshl_or_b32 v78, v78, 9, v1
	global_load_dwordx4 v[78:81], v78, s[0:1]
	s_branch .LBB0_1897
